# attention: staging loads at odd QK^T slots 5/13/21/29 (after the qb=1 MFMA and its K read)
# baseline (speedup 1.0000x reference)
; __device__ __forceinline__ void partialSM(f32x16& p0, f32x16& p1, float mC) {
;   (void)mC; (void)p1;
;   for (int r = 0; r < 16; ++r) p0[r] = __builtin_amdgcn_exp2f(p0[r]);
; }
; __device__ __forceinline__ void finishSM(f32x16& p0, f32x16& p1, float& l_reg, bf16x8& pa0, bf16x8& pa1, bf16x8& pa2, bf16x8& pa3) {
;   for (int r = 0; r < 16; ++r) p1[r] = __builtin_amdgcn_exp2f(p1[r]);
;   float ps = 0; for (int r = 0; r < 16; ++r) ps += p0[r]; for (int r = 0; r < 16; ++r) ps += p1[r];
;   { auto rr = __builtin_amdgcn_permlane32_swap(__float_as_uint(ps), __float_as_uint(ps), false, false);
;     ps = __uint_as_float(rr[0]) + __uint_as_float(rr[1]); }
;   l_reg += ps;
;     ...
;   PK4(p0, 0, pa0); PK4(p0, 8, pa1); PK4(p1, 0, pa2); PK4(p1, 8, pa3);
;     ...
; }
; __device__ __forceinline__ void qkt(f32x16& p0, f32x16& p1, const bf16* Ks, const bf16x8* qr, int r32, int hi, const f32x16& negm) {
; #pragma unroll
;   for (int d0 = 0; d0 < 8; ++d0) { int cb = (d0 * 16 + hi * 8) * 2;
;     bf16x8 b0 = *reinterpret_cast<const bf16x8*>((const char*)Ks + KSWZ(r32, cb));
;     bf16x8 b1 = *reinterpret_cast<const bf16x8*>((const char*)Ks + KSWZ(32 + r32, cb));
;     if (d0 == 0) { p0 = __builtin_amdgcn_mfma_f32_32x32x16_bf16(b0, qr[0], negm, 0, 0, 0); p1 = __builtin_amdgcn_mfma_f32_32x32x16_bf16(b1, qr[0], negm, 0, 0, 0); }
;     else { p0 = __builtin_amdgcn_mfma_f32_32x32x16_bf16(b0, qr[d0], p0, 0, 0, 0); p1 = __builtin_amdgcn_mfma_f32_32x32x16_bf16(b1, qr[d0], p1, 0, 0, 0); } }
; }
; __device__ __forceinline__ int v_st(int k, int c) { const int kk = (k & ~0xC) | ((k & 4) << 1) | ((k & 8) >> 1); return ((kk >> 3) * 4 + (c >> 5)) * 512 + ((kk & 7) * 32 + (c & 31)) * 2; }
; __device__ __forceinline__ int v_rd_base(int lane) { return ((lane & 3) << 3) | (((lane >> 2) & 3) << 6) | (((lane >> 4) & 1) << 5) | (((lane >> 5) & 1) << 8); }
; template <int OFF> __device__ __forceinline__ s16x4 tr_read(int vb) {
;   s16x4 r; asm volatile("ds_read_b64_tr_b16 %0, %1 offset:%2" : "=&v"(r) : "v"(vb), "i"(OFF) : "memory"); return r;
; }
; template <int D0> __device__ __forceinline__ void pv_one(f32x16& od, int vb, bf16x8 pa0, bf16x8 pa1, bf16x8 pa2, bf16x8 pa3) {
;   const s16x4 l0 = tr_read<v_rd_off(D0, 0, 0)>(vb), h0 = tr_read<v_rd_off(D0, 0, 1)>(vb), l1 = tr_read<v_rd_off(D0, 1, 0)>(vb), h1 = tr_read<v_rd_off(D0, 1, 1)>(vb);
.Lattn_loop:
	s_barrier
	s_waitcnt lgkmcnt(3)
	v_mfma_f32_16x16x32_bf16 v[114:117], v[178:181], v[146:149], v[2:5]
	v_add_f32_e32 v250, v82, v250
	s_add_u32 s98, s98, 0x8000
	s_addc_u32 s99, s99, 0
	s_add_u32 s100, s100, 0x8000
	s_addc_u32 s101, s101, 0
	v_mfma_f32_16x16x32_bf16 v[118:121], v[178:181], v[162:165], v[2:5]
	ds_read_b128 v[178:181], v235 offset:16384
	v_add_f32_e32 v250, v83, v250
	v_add_f32_e32 v250, v84, v250
	s_waitcnt lgkmcnt(3)
	v_mfma_f32_16x16x32_bf16 v[122:125], v[182:185], v[146:149], v[2:5]
	v_add_f32_e32 v250, v85, v250
	v_mfma_f32_16x16x32_bf16 v[126:129], v[182:185], v[162:165], v[2:5]
	ds_read_b128 v[182:185], v235 offset:20480
	v_add_f32_e32 v250, v90, v250
	v_add_f32_e32 v250, v91, v250
	s_waitcnt lgkmcnt(3)
	v_mfma_f32_16x16x32_bf16 v[130:133], v[186:189], v[146:149], v[2:5]
	v_add_f32_e32 v250, v92, v250
	v_mfma_f32_16x16x32_bf16 v[134:137], v[186:189], v[162:165], v[2:5]
	ds_read_b128 v[186:189], v235 offset:24576
	v_add_f32_e32 v250, v93, v250
	v_cvt_pk_bf16_f32 v82, v82, v83
	s_add_u32 m0, s79, 0
	s_nop 0
	global_load_lds_dwordx4 v246, s[98:99]
	s_waitcnt lgkmcnt(3)
	v_mfma_f32_16x16x32_bf16 v[138:141], v[190:193], v[146:149], v[2:5]
	v_cvt_pk_bf16_f32 v83, v84, v85
	v_mfma_f32_16x16x32_bf16 v[142:145], v[190:193], v[162:165], v[2:5]
	ds_read_b128 v[190:193], v235 offset:28672
	v_cvt_pk_bf16_f32 v84, v90, v91
	v_cvt_pk_bf16_f32 v85, v92, v93
	s_waitcnt lgkmcnt(3)
	v_mfma_f32_16x16x32_bf16 v[114:117], v[178:181], v[150:153], v[114:117]
	v_add_f32_e32 v251, v86, v251
	v_mfma_f32_16x16x32_bf16 v[118:121], v[178:181], v[166:169], v[118:121]
	ds_read_b128 v[178:181], v236 offset:16384
	v_add_f32_e32 v251, v87, v251
	v_add_f32_e32 v251, v88, v251
	s_waitcnt lgkmcnt(3)
	v_mfma_f32_16x16x32_bf16 v[122:125], v[182:185], v[150:153], v[122:125]
	v_add_f32_e32 v251, v89, v251
	v_mfma_f32_16x16x32_bf16 v[126:129], v[182:185], v[166:169], v[126:129]
	ds_read_b128 v[182:185], v236 offset:20480
	v_add_f32_e32 v251, v94, v251
	v_add_f32_e32 v251, v95, v251
	s_waitcnt lgkmcnt(3)
	v_mfma_f32_16x16x32_bf16 v[130:133], v[186:189], v[150:153], v[130:133]
	v_add_f32_e32 v251, v96, v251
	v_mfma_f32_16x16x32_bf16 v[134:137], v[186:189], v[166:169], v[134:137]
	ds_read_b128 v[186:189], v236 offset:24576
	v_add_f32_e32 v251, v97, v251
	v_cvt_pk_bf16_f32 v86, v86, v87
	s_add_u32 m0, s79, 1024
	s_nop 0
	global_load_lds_dwordx4 v247, s[98:99]
	s_waitcnt lgkmcnt(3)
	v_mfma_f32_16x16x32_bf16 v[138:141], v[190:193], v[150:153], v[138:141]
	v_cvt_pk_bf16_f32 v87, v88, v89
	v_mfma_f32_16x16x32_bf16 v[142:145], v[190:193], v[166:169], v[142:145]
	ds_read_b128 v[190:193], v236 offset:28672
	v_cvt_pk_bf16_f32 v88, v94, v95
	v_cvt_pk_bf16_f32 v89, v96, v97
	s_waitcnt lgkmcnt(3)
	v_mfma_f32_16x16x32_bf16 v[114:117], v[178:181], v[154:157], v[114:117]
	v_add_f32_e32 v250, v98, v250
	v_mfma_f32_16x16x32_bf16 v[118:121], v[178:181], v[170:173], v[118:121]
	ds_read_b128 v[178:181], v237 offset:16384
	v_add_f32_e32 v250, v99, v250
	v_add_f32_e32 v250, v100, v250
	s_waitcnt lgkmcnt(3)
	v_mfma_f32_16x16x32_bf16 v[122:125], v[182:185], v[154:157], v[122:125]
	v_add_f32_e32 v250, v101, v250
	v_mfma_f32_16x16x32_bf16 v[126:129], v[182:185], v[170:173], v[126:129]
	ds_read_b128 v[182:185], v237 offset:20480
	v_add_f32_e32 v250, v106, v250
	v_add_f32_e32 v250, v107, v250
	s_waitcnt lgkmcnt(3)
	v_mfma_f32_16x16x32_bf16 v[130:133], v[186:189], v[154:157], v[130:133]
	v_add_f32_e32 v250, v108, v250
	ds_read_b64_tr_b16 v[202:203], v238 offset:0
	ds_read_b64_tr_b16 v[204:205], v238 offset:4096
	v_mfma_f32_16x16x32_bf16 v[134:137], v[186:189], v[170:173], v[134:137]
	ds_read_b128 v[186:189], v237 offset:24576
	v_add_f32_e32 v250, v109, v250
	v_cvt_pk_bf16_f32 v98, v98, v99
	s_add_u32 m0, s80, 49152
	s_nop 0
	global_load_lds_dwordx4 v248, s[100:101]
	s_waitcnt lgkmcnt(5)
	v_mfma_f32_16x16x32_bf16 v[138:141], v[190:193], v[154:157], v[138:141]
	v_cvt_pk_bf16_f32 v99, v100, v101
	ds_read_b64_tr_b16 v[206:207], v239 offset:0
	ds_read_b64_tr_b16 v[208:209], v239 offset:4096
	v_mfma_f32_16x16x32_bf16 v[142:145], v[190:193], v[170:173], v[142:145]
	ds_read_b128 v[190:193], v237 offset:28672
	v_cvt_pk_bf16_f32 v100, v106, v107
	v_cvt_pk_bf16_f32 v101, v108, v109
	s_waitcnt lgkmcnt(7)
	v_mfma_f32_16x16x32_bf16 v[114:117], v[178:181], v[158:161], v[114:117]
	v_add_f32_e32 v251, v102, v251
	ds_read_b64_tr_b16 v[210:211], v240 offset:0
	ds_read_b64_tr_b16 v[212:213], v240 offset:4096
	v_mfma_f32_16x16x32_bf16 v[118:121], v[178:181], v[174:177], v[118:121]
	v_add_f32_e32 v251, v103, v251
	v_add_f32_e32 v251, v104, v251
	s_waitcnt lgkmcnt(8)
	v_mfma_f32_16x16x32_bf16 v[122:125], v[182:185], v[158:161], v[122:125]
	v_add_f32_e32 v251, v105, v251
	ds_read_b64_tr_b16 v[214:215], v241 offset:0
	ds_read_b64_tr_b16 v[216:217], v241 offset:4096
	v_mfma_f32_16x16x32_bf16 v[126:129], v[182:185], v[174:177], v[126:129]
	v_add_f32_e32 v251, v110, v251
	v_add_f32_e32 v251, v111, v251
	s_waitcnt lgkmcnt(7)
	v_mfma_f32_16x16x32_bf16 v[130:133], v[186:189], v[158:161], v[130:133]
	v_add_f32_e32 v251, v112, v251
	ds_read_b64_tr_b16 v[218:219], v242 offset:0
	ds_read_b64_tr_b16 v[220:221], v242 offset:4096
	v_mfma_f32_16x16x32_bf16 v[134:137], v[186:189], v[174:177], v[134:137]
	v_add_f32_e32 v251, v113, v251
	v_cvt_pk_bf16_f32 v102, v102, v103
	s_add_u32 m0, s80, 50176
	s_nop 0
	global_load_lds_dwordx4 v249, s[100:101]
	s_waitcnt lgkmcnt(6)
; __device__ __forceinline__ void partialSM(f32x16& p0, f32x16& p1, float mC) {
;   (void)mC; (void)p1;
;   for (int r = 0; r < 16; ++r) p0[r] = __builtin_amdgcn_exp2f(p0[r]);
; }
; __device__ __forceinline__ void finishSM(f32x16& p0, f32x16& p1, float& l_reg, bf16x8& pa0, bf16x8& pa1, bf16x8& pa2, bf16x8& pa3) {
;   for (int r = 0; r < 16; ++r) p1[r] = __builtin_amdgcn_exp2f(p1[r]);
;   float ps = 0; for (int r = 0; r < 16; ++r) ps += p0[r]; for (int r = 0; r < 16; ++r) ps += p1[r];
;   { auto rr = __builtin_amdgcn_permlane32_swap(__float_as_uint(ps), __float_as_uint(ps), false, false);
;     ps = __uint_as_float(rr[0]) + __uint_as_float(rr[1]); }
;   l_reg += ps;
;     ...
;   PK4(p0, 0, pa0); PK4(p0, 8, pa1); PK4(p1, 0, pa2); PK4(p1, 8, pa3);
;     ...
; }
; __device__ __forceinline__ void qkt(f32x16& p0, f32x16& p1, const bf16* Ks, const bf16x8* qr, int r32, int hi, const f32x16& negm) {
; #pragma unroll
;   for (int d0 = 0; d0 < 8; ++d0) { int cb = (d0 * 16 + hi * 8) * 2;
;     bf16x8 b0 = *reinterpret_cast<const bf16x8*>((const char*)Ks + KSWZ(r32, cb));
;     bf16x8 b1 = *reinterpret_cast<const bf16x8*>((const char*)Ks + KSWZ(32 + r32, cb));
;     if (d0 == 0) { p0 = __builtin_amdgcn_mfma_f32_32x32x16_bf16(b0, qr[0], negm, 0, 0, 0); p1 = __builtin_amdgcn_mfma_f32_32x32x16_bf16(b1, qr[0], negm, 0, 0, 0); }
;     else { p0 = __builtin_amdgcn_mfma_f32_32x32x16_bf16(b0, qr[d0], p0, 0, 0, 0); p1 = __builtin_amdgcn_mfma_f32_32x32x16_bf16(b1, qr[d0], p1, 0, 0, 0); } }
; }
; __device__ __forceinline__ int v_st(int k, int c) { const int kk = (k & ~0xC) | ((k & 4) << 1) | ((k & 8) >> 1); return ((kk >> 3) * 4 + (c >> 5)) * 512 + ((kk & 7) * 32 + (c & 31)) * 2; }
; __device__ __forceinline__ int v_rd_base(int lane) { return ((lane & 3) << 3) | (((lane >> 2) & 3) << 6) | (((lane >> 4) & 1) << 5) | (((lane >> 5) & 1) << 8); }
; template <int OFF> __device__ __forceinline__ s16x4 tr_read(int vb) {
;   s16x4 r; asm volatile("ds_read_b64_tr_b16 %0, %1 offset:%2" : "=&v"(r) : "v"(vb), "i"(OFF) : "memory"); return r;
; }
; template <int D0> __device__ __forceinline__ void pv_one(f32x16& od, int vb, bf16x8 pa0, bf16x8 pa1, bf16x8 pa2, bf16x8 pa3) {
;   const s16x4 l0 = tr_read<v_rd_off(D0, 0, 0)>(vb), h0 = tr_read<v_rd_off(D0, 0, 1)>(vb), l1 = tr_read<v_rd_off(D0, 1, 0)>(vb), h1 = tr_read<v_rd_off(D0, 1, 1)>(vb);
	v_mfma_f32_16x16x32_bf16 v[138:141], v[190:193], v[158:161], v[138:141]
	v_cvt_pk_bf16_f32 v103, v104, v105
	ds_read_b64_tr_b16 v[222:223], v243 offset:0
	ds_read_b64_tr_b16 v[224:225], v243 offset:4096
	v_mfma_f32_16x16x32_bf16 v[142:145], v[190:193], v[174:177], v[142:145]
	v_cvt_pk_bf16_f32 v104, v110, v111
	v_cvt_pk_bf16_f32 v105, v112, v113
	v_mfma_f32_16x16x32_bf16 v[18:21], v[202:205], v[82:85], v[18:21]
	v_exp_f32_e32 v114, v114
	v_mfma_f32_16x16x32_bf16 v[22:25], v[202:205], v[86:89], v[22:25]
	ds_read_b64_tr_b16 v[202:203], v244 offset:0
	ds_read_b64_tr_b16 v[204:205], v244 offset:4096
	v_exp_f32_e32 v115, v115
	v_mfma_f32_16x16x32_bf16 v[26:29], v[206:209], v[82:85], v[26:29]
	v_exp_f32_e32 v116, v116
	v_mfma_f32_16x16x32_bf16 v[30:33], v[206:209], v[86:89], v[30:33]
	ds_read_b64_tr_b16 v[206:207], v245 offset:0
	ds_read_b64_tr_b16 v[208:209], v245 offset:4096
	v_exp_f32_e32 v117, v117
	s_waitcnt lgkmcnt(10)
	v_mfma_f32_16x16x32_bf16 v[34:37], v[210:213], v[82:85], v[34:37]
	v_exp_f32_e32 v118, v118
	v_mfma_f32_16x16x32_bf16 v[38:41], v[210:213], v[86:89], v[38:41]
	ds_read_b64_tr_b16 v[210:211], v238 offset:8192
	ds_read_b64_tr_b16 v[212:213], v238 offset:12288
	v_exp_f32_e32 v119, v119
	s_waitcnt lgkmcnt(10)
	v_mfma_f32_16x16x32_bf16 v[42:45], v[214:217], v[82:85], v[42:45]
	v_exp_f32_e32 v120, v120
	v_mfma_f32_16x16x32_bf16 v[46:49], v[214:217], v[86:89], v[46:49]
	ds_read_b64_tr_b16 v[214:215], v239 offset:8192
	ds_read_b64_tr_b16 v[216:217], v239 offset:12288
	v_exp_f32_e32 v121, v121
	s_waitcnt lgkmcnt(10)
	v_mfma_f32_16x16x32_bf16 v[50:53], v[218:221], v[82:85], v[50:53]
	v_exp_f32_e32 v122, v122
	v_mfma_f32_16x16x32_bf16 v[54:57], v[218:221], v[86:89], v[54:57]
	ds_read_b64_tr_b16 v[218:219], v240 offset:8192
	ds_read_b64_tr_b16 v[220:221], v240 offset:12288
	v_exp_f32_e32 v123, v123
	s_waitcnt lgkmcnt(10)
	v_mfma_f32_16x16x32_bf16 v[58:61], v[222:225], v[82:85], v[58:61]
	v_exp_f32_e32 v124, v124
	v_mfma_f32_16x16x32_bf16 v[62:65], v[222:225], v[86:89], v[62:65]
	ds_read_b64_tr_b16 v[222:223], v241 offset:8192
	ds_read_b64_tr_b16 v[224:225], v241 offset:12288
	v_exp_f32_e32 v125, v125
	s_waitcnt lgkmcnt(10)
	v_mfma_f32_16x16x32_bf16 v[66:69], v[202:205], v[82:85], v[66:69]
	v_exp_f32_e32 v126, v126
	v_mfma_f32_16x16x32_bf16 v[70:73], v[202:205], v[86:89], v[70:73]
	ds_read_b64_tr_b16 v[202:203], v242 offset:8192
	ds_read_b64_tr_b16 v[204:205], v242 offset:12288
	v_exp_f32_e32 v127, v127
	s_waitcnt lgkmcnt(10)
	v_mfma_f32_16x16x32_bf16 v[74:77], v[206:209], v[82:85], v[74:77]
	v_exp_f32_e32 v128, v128
	v_mfma_f32_16x16x32_bf16 v[78:81], v[206:209], v[86:89], v[78:81]
	ds_read_b64_tr_b16 v[206:207], v243 offset:8192
	ds_read_b64_tr_b16 v[208:209], v243 offset:12288
	v_exp_f32_e32 v129, v129
	s_waitcnt lgkmcnt(10)
	v_mfma_f32_16x16x32_bf16 v[18:21], v[210:213], v[98:101], v[18:21]
	v_exp_f32_e32 v130, v130
	v_mfma_f32_16x16x32_bf16 v[22:25], v[210:213], v[102:105], v[22:25]
	ds_read_b64_tr_b16 v[210:211], v244 offset:8192
	ds_read_b64_tr_b16 v[212:213], v244 offset:12288
	v_exp_f32_e32 v131, v131
	s_waitcnt lgkmcnt(10)
	v_mfma_f32_16x16x32_bf16 v[26:29], v[214:217], v[98:101], v[26:29]
	v_exp_f32_e32 v132, v132
	v_mfma_f32_16x16x32_bf16 v[30:33], v[214:217], v[102:105], v[30:33]
	ds_read_b64_tr_b16 v[214:215], v245 offset:8192
	ds_read_b64_tr_b16 v[216:217], v245 offset:12288
	v_exp_f32_e32 v133, v133
	s_waitcnt lgkmcnt(10)
	v_mfma_f32_16x16x32_bf16 v[34:37], v[218:221], v[98:101], v[34:37]
	v_exp_f32_e32 v134, v134
	v_mfma_f32_16x16x32_bf16 v[38:41], v[218:221], v[102:105], v[38:41]
	v_exp_f32_e32 v135, v135
	s_waitcnt lgkmcnt(8)
	v_mfma_f32_16x16x32_bf16 v[42:45], v[222:225], v[98:101], v[42:45]
	v_exp_f32_e32 v136, v136
	v_mfma_f32_16x16x32_bf16 v[46:49], v[222:225], v[102:105], v[46:49]
	v_exp_f32_e32 v137, v137
	s_waitcnt lgkmcnt(6)
	v_mfma_f32_16x16x32_bf16 v[50:53], v[202:205], v[98:101], v[50:53]
	v_exp_f32_e32 v138, v138
	ds_read_b128 v[178:181], v234 offset:32768
	v_mfma_f32_16x16x32_bf16 v[54:57], v[202:205], v[102:105], v[54:57]
	v_exp_f32_e32 v139, v139
	s_waitcnt lgkmcnt(5)
	v_mfma_f32_16x16x32_bf16 v[58:61], v[206:209], v[98:101], v[58:61]
	v_exp_f32_e32 v140, v140
	ds_read_b128 v[182:185], v234 offset:36864
	v_mfma_f32_16x16x32_bf16 v[62:65], v[206:209], v[102:105], v[62:65]
	v_exp_f32_e32 v141, v141
	s_waitcnt lgkmcnt(4)
	v_mfma_f32_16x16x32_bf16 v[66:69], v[210:213], v[98:101], v[66:69]
	v_exp_f32_e32 v142, v142
	ds_read_b128 v[186:189], v234 offset:40960
	v_mfma_f32_16x16x32_bf16 v[70:73], v[210:213], v[102:105], v[70:73]
	v_exp_f32_e32 v143, v143
	s_waitcnt lgkmcnt(3)
	v_mfma_f32_16x16x32_bf16 v[74:77], v[214:217], v[98:101], v[74:77]
	v_exp_f32_e32 v144, v144
	ds_read_b128 v[190:193], v234 offset:45056
	v_mfma_f32_16x16x32_bf16 v[78:81], v[214:217], v[102:105], v[78:81]
	v_exp_f32_e32 v145, v145
	s_waitcnt vmcnt(4)
	s_barrier
; __device__ __forceinline__ void partialSM(f32x16& p0, f32x16& p1, float mC) {
;   (void)mC; (void)p1;
;   for (int r = 0; r < 16; ++r) p0[r] = __builtin_amdgcn_exp2f(p0[r]);
; }
; __device__ __forceinline__ void finishSM(f32x16& p0, f32x16& p1, float& l_reg, bf16x8& pa0, bf16x8& pa1, bf16x8& pa2, bf16x8& pa3) {
;   for (int r = 0; r < 16; ++r) p1[r] = __builtin_amdgcn_exp2f(p1[r]);
;   float ps = 0; for (int r = 0; r < 16; ++r) ps += p0[r]; for (int r = 0; r < 16; ++r) ps += p1[r];
;   { auto rr = __builtin_amdgcn_permlane32_swap(__float_as_uint(ps), __float_as_uint(ps), false, false);
;     ps = __uint_as_float(rr[0]) + __uint_as_float(rr[1]); }
;   l_reg += ps;
;     ...
;   PK4(p0, 0, pa0); PK4(p0, 8, pa1); PK4(p1, 0, pa2); PK4(p1, 8, pa3);
;     ...
; }
; __device__ __forceinline__ void qkt(f32x16& p0, f32x16& p1, const bf16* Ks, const bf16x8* qr, int r32, int hi, const f32x16& negm) {
; #pragma unroll
;   for (int d0 = 0; d0 < 8; ++d0) { int cb = (d0 * 16 + hi * 8) * 2;
;     bf16x8 b0 = *reinterpret_cast<const bf16x8*>((const char*)Ks + KSWZ(r32, cb));
;     bf16x8 b1 = *reinterpret_cast<const bf16x8*>((const char*)Ks + KSWZ(32 + r32, cb));
;     if (d0 == 0) { p0 = __builtin_amdgcn_mfma_f32_32x32x16_bf16(b0, qr[0], negm, 0, 0, 0); p1 = __builtin_amdgcn_mfma_f32_32x32x16_bf16(b1, qr[0], negm, 0, 0, 0); }
;     else { p0 = __builtin_amdgcn_mfma_f32_32x32x16_bf16(b0, qr[d0], p0, 0, 0, 0); p1 = __builtin_amdgcn_mfma_f32_32x32x16_bf16(b1, qr[d0], p1, 0, 0, 0); } }
; }
; __device__ __forceinline__ int v_st(int k, int c) { const int kk = (k & ~0xC) | ((k & 4) << 1) | ((k & 8) >> 1); return ((kk >> 3) * 4 + (c >> 5)) * 512 + ((kk & 7) * 32 + (c & 31)) * 2; }
; __device__ __forceinline__ int v_rd_base(int lane) { return ((lane & 3) << 3) | (((lane >> 2) & 3) << 6) | (((lane >> 4) & 1) << 5) | (((lane >> 5) & 1) << 8); }
; template <int OFF> __device__ __forceinline__ s16x4 tr_read(int vb) {
;   s16x4 r; asm volatile("ds_read_b64_tr_b16 %0, %1 offset:%2" : "=&v"(r) : "v"(vb), "i"(OFF) : "memory"); return r;
; }
; template <int D0> __device__ __forceinline__ void pv_one(f32x16& od, int vb, bf16x8 pa0, bf16x8 pa1, bf16x8 pa2, bf16x8 pa3) {
;   const s16x4 l0 = tr_read<v_rd_off(D0, 0, 0)>(vb), h0 = tr_read<v_rd_off(D0, 0, 1)>(vb), l1 = tr_read<v_rd_off(D0, 1, 0)>(vb), h1 = tr_read<v_rd_off(D0, 1, 1)>(vb);
	s_waitcnt lgkmcnt(3)
	v_mfma_f32_16x16x32_bf16 v[82:85], v[178:181], v[146:149], v[2:5]
	v_add_f32_e32 v250, v114, v250
	s_add_u32 s98, s98, 0x8000
	s_addc_u32 s99, s99, 0
	s_add_u32 s100, s100, 0x8000
	s_addc_u32 s101, s101, 0
	v_mfma_f32_16x16x32_bf16 v[86:89], v[178:181], v[162:165], v[2:5]
	ds_read_b128 v[178:181], v235 offset:32768
	v_add_f32_e32 v250, v115, v250
	v_add_f32_e32 v250, v116, v250
	s_waitcnt lgkmcnt(3)
	v_mfma_f32_16x16x32_bf16 v[90:93], v[182:185], v[146:149], v[2:5]
	v_add_f32_e32 v250, v117, v250
	v_mfma_f32_16x16x32_bf16 v[94:97], v[182:185], v[162:165], v[2:5]
	ds_read_b128 v[182:185], v235 offset:36864
	v_add_f32_e32 v250, v122, v250
	v_add_f32_e32 v250, v123, v250
	s_waitcnt lgkmcnt(3)
	v_mfma_f32_16x16x32_bf16 v[98:101], v[186:189], v[146:149], v[2:5]
	v_add_f32_e32 v250, v124, v250
	v_mfma_f32_16x16x32_bf16 v[102:105], v[186:189], v[162:165], v[2:5]
	ds_read_b128 v[186:189], v235 offset:40960
	v_add_f32_e32 v250, v125, v250
	v_cvt_pk_bf16_f32 v114, v114, v115
	s_add_u32 m0, s79, 16384
	s_nop 0
	global_load_lds_dwordx4 v246, s[98:99]
	s_waitcnt lgkmcnt(3)
	v_mfma_f32_16x16x32_bf16 v[106:109], v[190:193], v[146:149], v[2:5]
	v_cvt_pk_bf16_f32 v115, v116, v117
	v_mfma_f32_16x16x32_bf16 v[110:113], v[190:193], v[162:165], v[2:5]
	ds_read_b128 v[190:193], v235 offset:45056
	v_cvt_pk_bf16_f32 v116, v122, v123
	v_cvt_pk_bf16_f32 v117, v124, v125
	s_waitcnt lgkmcnt(3)
	v_mfma_f32_16x16x32_bf16 v[82:85], v[178:181], v[150:153], v[82:85]
	v_add_f32_e32 v251, v118, v251
	v_mfma_f32_16x16x32_bf16 v[86:89], v[178:181], v[166:169], v[86:89]
	ds_read_b128 v[178:181], v236 offset:32768
	v_add_f32_e32 v251, v119, v251
	v_add_f32_e32 v251, v120, v251
	s_waitcnt lgkmcnt(3)
	v_mfma_f32_16x16x32_bf16 v[90:93], v[182:185], v[150:153], v[90:93]
	v_add_f32_e32 v251, v121, v251
	v_mfma_f32_16x16x32_bf16 v[94:97], v[182:185], v[166:169], v[94:97]
	ds_read_b128 v[182:185], v236 offset:36864
	v_add_f32_e32 v251, v126, v251
	v_add_f32_e32 v251, v127, v251
	s_waitcnt lgkmcnt(3)
	v_mfma_f32_16x16x32_bf16 v[98:101], v[186:189], v[150:153], v[98:101]
	v_add_f32_e32 v251, v128, v251
	v_mfma_f32_16x16x32_bf16 v[102:105], v[186:189], v[166:169], v[102:105]
	ds_read_b128 v[186:189], v236 offset:40960
	v_add_f32_e32 v251, v129, v251
	v_cvt_pk_bf16_f32 v118, v118, v119
	s_add_u32 m0, s79, 17408
	s_nop 0
	global_load_lds_dwordx4 v247, s[98:99]
	s_waitcnt lgkmcnt(3)
	v_mfma_f32_16x16x32_bf16 v[106:109], v[190:193], v[150:153], v[106:109]
	v_cvt_pk_bf16_f32 v119, v120, v121
	v_mfma_f32_16x16x32_bf16 v[110:113], v[190:193], v[166:169], v[110:113]
	ds_read_b128 v[190:193], v236 offset:45056
	v_cvt_pk_bf16_f32 v120, v126, v127
	v_cvt_pk_bf16_f32 v121, v128, v129
	s_waitcnt lgkmcnt(3)
	v_mfma_f32_16x16x32_bf16 v[82:85], v[178:181], v[154:157], v[82:85]
	v_add_f32_e32 v250, v130, v250
	v_mfma_f32_16x16x32_bf16 v[86:89], v[178:181], v[170:173], v[86:89]
	ds_read_b128 v[178:181], v237 offset:32768
	v_add_f32_e32 v250, v131, v250
	v_add_f32_e32 v250, v132, v250
	s_waitcnt lgkmcnt(3)
	v_mfma_f32_16x16x32_bf16 v[90:93], v[182:185], v[154:157], v[90:93]
	v_add_f32_e32 v250, v133, v250
	v_mfma_f32_16x16x32_bf16 v[94:97], v[182:185], v[170:173], v[94:97]
	ds_read_b128 v[182:185], v237 offset:36864
	v_add_f32_e32 v250, v138, v250
	v_add_f32_e32 v250, v139, v250
	s_waitcnt lgkmcnt(3)
	v_mfma_f32_16x16x32_bf16 v[98:101], v[186:189], v[154:157], v[98:101]
	v_add_f32_e32 v250, v140, v250
	ds_read_b64_tr_b16 v[202:203], v238 offset:16384
	ds_read_b64_tr_b16 v[204:205], v238 offset:20480
	v_mfma_f32_16x16x32_bf16 v[102:105], v[186:189], v[170:173], v[102:105]
	ds_read_b128 v[186:189], v237 offset:40960
	v_add_f32_e32 v250, v141, v250
	v_cvt_pk_bf16_f32 v130, v130, v131
	s_add_u32 m0, s80, 0
	s_nop 0
	global_load_lds_dwordx4 v248, s[100:101]
	s_waitcnt lgkmcnt(5)
	v_mfma_f32_16x16x32_bf16 v[106:109], v[190:193], v[154:157], v[106:109]
	v_cvt_pk_bf16_f32 v131, v132, v133
	ds_read_b64_tr_b16 v[206:207], v239 offset:16384
	ds_read_b64_tr_b16 v[208:209], v239 offset:20480
	v_mfma_f32_16x16x32_bf16 v[110:113], v[190:193], v[170:173], v[110:113]
	ds_read_b128 v[190:193], v237 offset:45056
	v_cvt_pk_bf16_f32 v132, v138, v139
	v_cvt_pk_bf16_f32 v133, v140, v141
	s_waitcnt lgkmcnt(7)
	v_mfma_f32_16x16x32_bf16 v[82:85], v[178:181], v[158:161], v[82:85]
	v_add_f32_e32 v251, v134, v251
	ds_read_b64_tr_b16 v[210:211], v240 offset:16384
	ds_read_b64_tr_b16 v[212:213], v240 offset:20480
	v_mfma_f32_16x16x32_bf16 v[86:89], v[178:181], v[174:177], v[86:89]
	v_add_f32_e32 v251, v135, v251
	v_add_f32_e32 v251, v136, v251
	s_waitcnt lgkmcnt(8)
	v_mfma_f32_16x16x32_bf16 v[90:93], v[182:185], v[158:161], v[90:93]
	v_add_f32_e32 v251, v137, v251
	ds_read_b64_tr_b16 v[214:215], v241 offset:16384
	ds_read_b64_tr_b16 v[216:217], v241 offset:20480
	v_mfma_f32_16x16x32_bf16 v[94:97], v[182:185], v[174:177], v[94:97]
	v_add_f32_e32 v251, v142, v251
	v_add_f32_e32 v251, v143, v251
	s_waitcnt lgkmcnt(7)
	v_mfma_f32_16x16x32_bf16 v[98:101], v[186:189], v[158:161], v[98:101]
	v_add_f32_e32 v251, v144, v251
	ds_read_b64_tr_b16 v[218:219], v242 offset:16384
	ds_read_b64_tr_b16 v[220:221], v242 offset:20480
	v_mfma_f32_16x16x32_bf16 v[102:105], v[186:189], v[174:177], v[102:105]
	v_add_f32_e32 v251, v145, v251
	v_cvt_pk_bf16_f32 v134, v134, v135
	s_add_u32 m0, s80, 1024
	s_nop 0
	global_load_lds_dwordx4 v249, s[100:101]
	s_waitcnt lgkmcnt(6)
; __device__ __forceinline__ void partialSM(f32x16& p0, f32x16& p1, float mC) {
;   (void)mC; (void)p1;
;   for (int r = 0; r < 16; ++r) p0[r] = __builtin_amdgcn_exp2f(p0[r]);
; }
; __device__ __forceinline__ void finishSM(f32x16& p0, f32x16& p1, float& l_reg, bf16x8& pa0, bf16x8& pa1, bf16x8& pa2, bf16x8& pa3) {
;   for (int r = 0; r < 16; ++r) p1[r] = __builtin_amdgcn_exp2f(p1[r]);
;   float ps = 0; for (int r = 0; r < 16; ++r) ps += p0[r]; for (int r = 0; r < 16; ++r) ps += p1[r];
;   { auto rr = __builtin_amdgcn_permlane32_swap(__float_as_uint(ps), __float_as_uint(ps), false, false);
;     ps = __uint_as_float(rr[0]) + __uint_as_float(rr[1]); }
;   l_reg += ps;
;     ...
;   PK4(p0, 0, pa0); PK4(p0, 8, pa1); PK4(p1, 0, pa2); PK4(p1, 8, pa3);
;     ...
; }
; __device__ __forceinline__ void qkt(f32x16& p0, f32x16& p1, const bf16* Ks, const bf16x8* qr, int r32, int hi, const f32x16& negm) {
; #pragma unroll
;   for (int d0 = 0; d0 < 8; ++d0) { int cb = (d0 * 16 + hi * 8) * 2;
;     bf16x8 b0 = *reinterpret_cast<const bf16x8*>((const char*)Ks + KSWZ(r32, cb));
;     bf16x8 b1 = *reinterpret_cast<const bf16x8*>((const char*)Ks + KSWZ(32 + r32, cb));
;     if (d0 == 0) { p0 = __builtin_amdgcn_mfma_f32_32x32x16_bf16(b0, qr[0], negm, 0, 0, 0); p1 = __builtin_amdgcn_mfma_f32_32x32x16_bf16(b1, qr[0], negm, 0, 0, 0); }
;     else { p0 = __builtin_amdgcn_mfma_f32_32x32x16_bf16(b0, qr[d0], p0, 0, 0, 0); p1 = __builtin_amdgcn_mfma_f32_32x32x16_bf16(b1, qr[d0], p1, 0, 0, 0); } }
; }
; __device__ __forceinline__ int v_st(int k, int c) { const int kk = (k & ~0xC) | ((k & 4) << 1) | ((k & 8) >> 1); return ((kk >> 3) * 4 + (c >> 5)) * 512 + ((kk & 7) * 32 + (c & 31)) * 2; }
; __device__ __forceinline__ int v_rd_base(int lane) { return ((lane & 3) << 3) | (((lane >> 2) & 3) << 6) | (((lane >> 4) & 1) << 5) | (((lane >> 5) & 1) << 8); }
; template <int OFF> __device__ __forceinline__ s16x4 tr_read(int vb) {
;   s16x4 r; asm volatile("ds_read_b64_tr_b16 %0, %1 offset:%2" : "=&v"(r) : "v"(vb), "i"(OFF) : "memory"); return r;
; }
; template <int D0> __device__ __forceinline__ void pv_one(f32x16& od, int vb, bf16x8 pa0, bf16x8 pa1, bf16x8 pa2, bf16x8 pa3) {
;   const s16x4 l0 = tr_read<v_rd_off(D0, 0, 0)>(vb), h0 = tr_read<v_rd_off(D0, 0, 1)>(vb), l1 = tr_read<v_rd_off(D0, 1, 0)>(vb), h1 = tr_read<v_rd_off(D0, 1, 1)>(vb);
	v_mfma_f32_16x16x32_bf16 v[106:109], v[190:193], v[158:161], v[106:109]
	v_cvt_pk_bf16_f32 v135, v136, v137
	ds_read_b64_tr_b16 v[222:223], v243 offset:16384
	ds_read_b64_tr_b16 v[224:225], v243 offset:20480
	v_mfma_f32_16x16x32_bf16 v[110:113], v[190:193], v[174:177], v[110:113]
	v_cvt_pk_bf16_f32 v136, v142, v143
	v_cvt_pk_bf16_f32 v137, v144, v145
	v_mfma_f32_16x16x32_bf16 v[18:21], v[202:205], v[114:117], v[18:21]
	v_exp_f32_e32 v82, v82
	v_mfma_f32_16x16x32_bf16 v[22:25], v[202:205], v[118:121], v[22:25]
	ds_read_b64_tr_b16 v[202:203], v244 offset:16384
	ds_read_b64_tr_b16 v[204:205], v244 offset:20480
	v_exp_f32_e32 v83, v83
	v_mfma_f32_16x16x32_bf16 v[26:29], v[206:209], v[114:117], v[26:29]
	v_exp_f32_e32 v84, v84
	v_mfma_f32_16x16x32_bf16 v[30:33], v[206:209], v[118:121], v[30:33]
	ds_read_b64_tr_b16 v[206:207], v245 offset:16384
	ds_read_b64_tr_b16 v[208:209], v245 offset:20480
	v_exp_f32_e32 v85, v85
	s_waitcnt lgkmcnt(10)
	v_mfma_f32_16x16x32_bf16 v[34:37], v[210:213], v[114:117], v[34:37]
	v_exp_f32_e32 v86, v86
	v_mfma_f32_16x16x32_bf16 v[38:41], v[210:213], v[118:121], v[38:41]
	ds_read_b64_tr_b16 v[210:211], v238 offset:24576
	ds_read_b64_tr_b16 v[212:213], v238 offset:28672
	v_exp_f32_e32 v87, v87
	s_waitcnt lgkmcnt(10)
	v_mfma_f32_16x16x32_bf16 v[42:45], v[214:217], v[114:117], v[42:45]
	v_exp_f32_e32 v88, v88
	v_mfma_f32_16x16x32_bf16 v[46:49], v[214:217], v[118:121], v[46:49]
	ds_read_b64_tr_b16 v[214:215], v239 offset:24576
	ds_read_b64_tr_b16 v[216:217], v239 offset:28672
	v_exp_f32_e32 v89, v89
	s_waitcnt lgkmcnt(10)
	v_mfma_f32_16x16x32_bf16 v[50:53], v[218:221], v[114:117], v[50:53]
	v_exp_f32_e32 v90, v90
	v_mfma_f32_16x16x32_bf16 v[54:57], v[218:221], v[118:121], v[54:57]
	ds_read_b64_tr_b16 v[218:219], v240 offset:24576
	ds_read_b64_tr_b16 v[220:221], v240 offset:28672
	v_exp_f32_e32 v91, v91
	s_waitcnt lgkmcnt(10)
	v_mfma_f32_16x16x32_bf16 v[58:61], v[222:225], v[114:117], v[58:61]
	v_exp_f32_e32 v92, v92
	v_mfma_f32_16x16x32_bf16 v[62:65], v[222:225], v[118:121], v[62:65]
	ds_read_b64_tr_b16 v[222:223], v241 offset:24576
	ds_read_b64_tr_b16 v[224:225], v241 offset:28672
	v_exp_f32_e32 v93, v93
	s_waitcnt lgkmcnt(10)
	v_mfma_f32_16x16x32_bf16 v[66:69], v[202:205], v[114:117], v[66:69]
	v_exp_f32_e32 v94, v94
	v_mfma_f32_16x16x32_bf16 v[70:73], v[202:205], v[118:121], v[70:73]
	ds_read_b64_tr_b16 v[202:203], v242 offset:24576
	ds_read_b64_tr_b16 v[204:205], v242 offset:28672
	v_exp_f32_e32 v95, v95
	s_waitcnt lgkmcnt(10)
	v_mfma_f32_16x16x32_bf16 v[74:77], v[206:209], v[114:117], v[74:77]
	v_exp_f32_e32 v96, v96
	v_mfma_f32_16x16x32_bf16 v[78:81], v[206:209], v[118:121], v[78:81]
	ds_read_b64_tr_b16 v[206:207], v243 offset:24576
	ds_read_b64_tr_b16 v[208:209], v243 offset:28672
	v_exp_f32_e32 v97, v97
	s_waitcnt lgkmcnt(10)
	v_mfma_f32_16x16x32_bf16 v[18:21], v[210:213], v[130:133], v[18:21]
	v_exp_f32_e32 v98, v98
	v_mfma_f32_16x16x32_bf16 v[22:25], v[210:213], v[134:137], v[22:25]
	ds_read_b64_tr_b16 v[210:211], v244 offset:24576
	ds_read_b64_tr_b16 v[212:213], v244 offset:28672
	v_exp_f32_e32 v99, v99
	s_waitcnt lgkmcnt(10)
	v_mfma_f32_16x16x32_bf16 v[26:29], v[214:217], v[130:133], v[26:29]
	v_exp_f32_e32 v100, v100
	v_mfma_f32_16x16x32_bf16 v[30:33], v[214:217], v[134:137], v[30:33]
	ds_read_b64_tr_b16 v[214:215], v245 offset:24576
	ds_read_b64_tr_b16 v[216:217], v245 offset:28672
	v_exp_f32_e32 v101, v101
	s_waitcnt lgkmcnt(10)
	v_mfma_f32_16x16x32_bf16 v[34:37], v[218:221], v[130:133], v[34:37]
	v_exp_f32_e32 v102, v102
	v_mfma_f32_16x16x32_bf16 v[38:41], v[218:221], v[134:137], v[38:41]
	v_exp_f32_e32 v103, v103
	s_waitcnt lgkmcnt(8)
	v_mfma_f32_16x16x32_bf16 v[42:45], v[222:225], v[130:133], v[42:45]
	v_exp_f32_e32 v104, v104
	v_mfma_f32_16x16x32_bf16 v[46:49], v[222:225], v[134:137], v[46:49]
	v_exp_f32_e32 v105, v105
	s_waitcnt lgkmcnt(6)
	v_mfma_f32_16x16x32_bf16 v[50:53], v[202:205], v[130:133], v[50:53]
	v_exp_f32_e32 v106, v106
	ds_read_b128 v[178:181], v234 offset:49152
	v_mfma_f32_16x16x32_bf16 v[54:57], v[202:205], v[134:137], v[54:57]
	v_exp_f32_e32 v107, v107
	s_waitcnt lgkmcnt(5)
	v_mfma_f32_16x16x32_bf16 v[58:61], v[206:209], v[130:133], v[58:61]
	v_exp_f32_e32 v108, v108
	ds_read_b128 v[182:185], v234 offset:53248
	v_mfma_f32_16x16x32_bf16 v[62:65], v[206:209], v[134:137], v[62:65]
	v_exp_f32_e32 v109, v109
	s_waitcnt lgkmcnt(4)
	v_mfma_f32_16x16x32_bf16 v[66:69], v[210:213], v[130:133], v[66:69]
	v_exp_f32_e32 v110, v110
	ds_read_b128 v[186:189], v234 offset:57344
	v_mfma_f32_16x16x32_bf16 v[70:73], v[210:213], v[134:137], v[70:73]
	v_exp_f32_e32 v111, v111
	s_waitcnt lgkmcnt(3)
	v_mfma_f32_16x16x32_bf16 v[74:77], v[214:217], v[130:133], v[74:77]
	v_exp_f32_e32 v112, v112
	ds_read_b128 v[190:193], v234 offset:61440
	v_mfma_f32_16x16x32_bf16 v[78:81], v[214:217], v[134:137], v[78:81]
	v_exp_f32_e32 v113, v113
	s_waitcnt vmcnt(4)
	s_barrier
; __device__ __forceinline__ void partialSM(f32x16& p0, f32x16& p1, float mC) {
;   (void)mC; (void)p1;
;   for (int r = 0; r < 16; ++r) p0[r] = __builtin_amdgcn_exp2f(p0[r]);
; }
; __device__ __forceinline__ void finishSM(f32x16& p0, f32x16& p1, float& l_reg, bf16x8& pa0, bf16x8& pa1, bf16x8& pa2, bf16x8& pa3) {
;   for (int r = 0; r < 16; ++r) p1[r] = __builtin_amdgcn_exp2f(p1[r]);
;   float ps = 0; for (int r = 0; r < 16; ++r) ps += p0[r]; for (int r = 0; r < 16; ++r) ps += p1[r];
;   { auto rr = __builtin_amdgcn_permlane32_swap(__float_as_uint(ps), __float_as_uint(ps), false, false);
;     ps = __uint_as_float(rr[0]) + __uint_as_float(rr[1]); }
;   l_reg += ps;
;     ...
;   PK4(p0, 0, pa0); PK4(p0, 8, pa1); PK4(p1, 0, pa2); PK4(p1, 8, pa3);
;     ...
; }
; __device__ __forceinline__ void qkt(f32x16& p0, f32x16& p1, const bf16* Ks, const bf16x8* qr, int r32, int hi, const f32x16& negm) {
; #pragma unroll
;   for (int d0 = 0; d0 < 8; ++d0) { int cb = (d0 * 16 + hi * 8) * 2;
;     bf16x8 b0 = *reinterpret_cast<const bf16x8*>((const char*)Ks + KSWZ(r32, cb));
;     bf16x8 b1 = *reinterpret_cast<const bf16x8*>((const char*)Ks + KSWZ(32 + r32, cb));
;     if (d0 == 0) { p0 = __builtin_amdgcn_mfma_f32_32x32x16_bf16(b0, qr[0], negm, 0, 0, 0); p1 = __builtin_amdgcn_mfma_f32_32x32x16_bf16(b1, qr[0], negm, 0, 0, 0); }
;     else { p0 = __builtin_amdgcn_mfma_f32_32x32x16_bf16(b0, qr[d0], p0, 0, 0, 0); p1 = __builtin_amdgcn_mfma_f32_32x32x16_bf16(b1, qr[d0], p1, 0, 0, 0); } }
; }
; __device__ __forceinline__ int v_st(int k, int c) { const int kk = (k & ~0xC) | ((k & 4) << 1) | ((k & 8) >> 1); return ((kk >> 3) * 4 + (c >> 5)) * 512 + ((kk & 7) * 32 + (c & 31)) * 2; }
; __device__ __forceinline__ int v_rd_base(int lane) { return ((lane & 3) << 3) | (((lane >> 2) & 3) << 6) | (((lane >> 4) & 1) << 5) | (((lane >> 5) & 1) << 8); }
; template <int OFF> __device__ __forceinline__ s16x4 tr_read(int vb) {
;   s16x4 r; asm volatile("ds_read_b64_tr_b16 %0, %1 offset:%2" : "=&v"(r) : "v"(vb), "i"(OFF) : "memory"); return r;
; }
; template <int D0> __device__ __forceinline__ void pv_one(f32x16& od, int vb, bf16x8 pa0, bf16x8 pa1, bf16x8 pa2, bf16x8 pa3) {
;   const s16x4 l0 = tr_read<v_rd_off(D0, 0, 0)>(vb), h0 = tr_read<v_rd_off(D0, 0, 1)>(vb), l1 = tr_read<v_rd_off(D0, 1, 0)>(vb), h1 = tr_read<v_rd_off(D0, 1, 1)>(vb);
	s_waitcnt lgkmcnt(3)
	v_mfma_f32_16x16x32_bf16 v[114:117], v[178:181], v[146:149], v[2:5]
	v_add_f32_e32 v250, v82, v250
	s_add_u32 s98, s98, 0x8000
	s_addc_u32 s99, s99, 0
	s_add_u32 s100, s100, 0x8000
	s_addc_u32 s101, s101, 0
	v_mfma_f32_16x16x32_bf16 v[118:121], v[178:181], v[162:165], v[2:5]
	ds_read_b128 v[178:181], v235 offset:49152
	v_add_f32_e32 v250, v83, v250
	v_add_f32_e32 v250, v84, v250
	s_waitcnt lgkmcnt(3)
	v_mfma_f32_16x16x32_bf16 v[122:125], v[182:185], v[146:149], v[2:5]
	v_add_f32_e32 v250, v85, v250
	v_mfma_f32_16x16x32_bf16 v[126:129], v[182:185], v[162:165], v[2:5]
	ds_read_b128 v[182:185], v235 offset:53248
	v_add_f32_e32 v250, v90, v250
	v_add_f32_e32 v250, v91, v250
	s_waitcnt lgkmcnt(3)
	v_mfma_f32_16x16x32_bf16 v[130:133], v[186:189], v[146:149], v[2:5]
	v_add_f32_e32 v250, v92, v250
	v_mfma_f32_16x16x32_bf16 v[134:137], v[186:189], v[162:165], v[2:5]
	ds_read_b128 v[186:189], v235 offset:57344
	v_add_f32_e32 v250, v93, v250
	v_cvt_pk_bf16_f32 v82, v82, v83
	s_add_u32 m0, s79, 32768
	s_nop 0
	global_load_lds_dwordx4 v246, s[98:99]
	s_waitcnt lgkmcnt(3)
	v_mfma_f32_16x16x32_bf16 v[138:141], v[190:193], v[146:149], v[2:5]
	v_cvt_pk_bf16_f32 v83, v84, v85
	v_mfma_f32_16x16x32_bf16 v[142:145], v[190:193], v[162:165], v[2:5]
	ds_read_b128 v[190:193], v235 offset:61440
	v_cvt_pk_bf16_f32 v84, v90, v91
	v_cvt_pk_bf16_f32 v85, v92, v93
	s_waitcnt lgkmcnt(3)
	v_mfma_f32_16x16x32_bf16 v[114:117], v[178:181], v[150:153], v[114:117]
	v_add_f32_e32 v251, v86, v251
	v_mfma_f32_16x16x32_bf16 v[118:121], v[178:181], v[166:169], v[118:121]
	ds_read_b128 v[178:181], v236 offset:49152
	v_add_f32_e32 v251, v87, v251
	v_add_f32_e32 v251, v88, v251
	s_waitcnt lgkmcnt(3)
	v_mfma_f32_16x16x32_bf16 v[122:125], v[182:185], v[150:153], v[122:125]
	v_add_f32_e32 v251, v89, v251
	v_mfma_f32_16x16x32_bf16 v[126:129], v[182:185], v[166:169], v[126:129]
	ds_read_b128 v[182:185], v236 offset:53248
	v_add_f32_e32 v251, v94, v251
	v_add_f32_e32 v251, v95, v251
	s_waitcnt lgkmcnt(3)
	v_mfma_f32_16x16x32_bf16 v[130:133], v[186:189], v[150:153], v[130:133]
	v_add_f32_e32 v251, v96, v251
	v_mfma_f32_16x16x32_bf16 v[134:137], v[186:189], v[166:169], v[134:137]
	ds_read_b128 v[186:189], v236 offset:57344
	v_add_f32_e32 v251, v97, v251
	v_cvt_pk_bf16_f32 v86, v86, v87
	s_add_u32 m0, s79, 33792
	s_nop 0
	global_load_lds_dwordx4 v247, s[98:99]
	s_waitcnt lgkmcnt(3)
	v_mfma_f32_16x16x32_bf16 v[138:141], v[190:193], v[150:153], v[138:141]
	v_cvt_pk_bf16_f32 v87, v88, v89
	v_mfma_f32_16x16x32_bf16 v[142:145], v[190:193], v[166:169], v[142:145]
	ds_read_b128 v[190:193], v236 offset:61440
	v_cvt_pk_bf16_f32 v88, v94, v95
	v_cvt_pk_bf16_f32 v89, v96, v97
	s_waitcnt lgkmcnt(3)
	v_mfma_f32_16x16x32_bf16 v[114:117], v[178:181], v[154:157], v[114:117]
	v_add_f32_e32 v250, v98, v250
	v_mfma_f32_16x16x32_bf16 v[118:121], v[178:181], v[170:173], v[118:121]
	ds_read_b128 v[178:181], v237 offset:49152
	v_add_f32_e32 v250, v99, v250
	v_add_f32_e32 v250, v100, v250
	s_waitcnt lgkmcnt(3)
	v_mfma_f32_16x16x32_bf16 v[122:125], v[182:185], v[154:157], v[122:125]
	v_add_f32_e32 v250, v101, v250
	v_mfma_f32_16x16x32_bf16 v[126:129], v[182:185], v[170:173], v[126:129]
	ds_read_b128 v[182:185], v237 offset:53248
	v_add_f32_e32 v250, v106, v250
	v_add_f32_e32 v250, v107, v250
	s_waitcnt lgkmcnt(3)
	v_mfma_f32_16x16x32_bf16 v[130:133], v[186:189], v[154:157], v[130:133]
	v_add_f32_e32 v250, v108, v250
	ds_read_b64_tr_b16 v[202:203], v238 offset:32768
	ds_read_b64_tr_b16 v[204:205], v238 offset:36864
	v_mfma_f32_16x16x32_bf16 v[134:137], v[186:189], v[170:173], v[134:137]
	ds_read_b128 v[186:189], v237 offset:57344
	v_add_f32_e32 v250, v109, v250
	v_cvt_pk_bf16_f32 v98, v98, v99
	s_add_u32 m0, s80, 16384
	s_nop 0
	global_load_lds_dwordx4 v248, s[100:101]
	s_waitcnt lgkmcnt(5)
	v_mfma_f32_16x16x32_bf16 v[138:141], v[190:193], v[154:157], v[138:141]
	v_cvt_pk_bf16_f32 v99, v100, v101
	ds_read_b64_tr_b16 v[206:207], v239 offset:32768
	ds_read_b64_tr_b16 v[208:209], v239 offset:36864
	v_mfma_f32_16x16x32_bf16 v[142:145], v[190:193], v[170:173], v[142:145]
	ds_read_b128 v[190:193], v237 offset:61440
	v_cvt_pk_bf16_f32 v100, v106, v107
	v_cvt_pk_bf16_f32 v101, v108, v109
	s_waitcnt lgkmcnt(7)
	v_mfma_f32_16x16x32_bf16 v[114:117], v[178:181], v[158:161], v[114:117]
	v_add_f32_e32 v251, v102, v251
	ds_read_b64_tr_b16 v[210:211], v240 offset:32768
	ds_read_b64_tr_b16 v[212:213], v240 offset:36864
	v_mfma_f32_16x16x32_bf16 v[118:121], v[178:181], v[174:177], v[118:121]
	v_add_f32_e32 v251, v103, v251
	v_add_f32_e32 v251, v104, v251
	s_waitcnt lgkmcnt(8)
	v_mfma_f32_16x16x32_bf16 v[122:125], v[182:185], v[158:161], v[122:125]
	v_add_f32_e32 v251, v105, v251
	ds_read_b64_tr_b16 v[214:215], v241 offset:32768
	ds_read_b64_tr_b16 v[216:217], v241 offset:36864
	v_mfma_f32_16x16x32_bf16 v[126:129], v[182:185], v[174:177], v[126:129]
	v_add_f32_e32 v251, v110, v251
	v_add_f32_e32 v251, v111, v251
	s_waitcnt lgkmcnt(7)
	v_mfma_f32_16x16x32_bf16 v[130:133], v[186:189], v[158:161], v[130:133]
	v_add_f32_e32 v251, v112, v251
	ds_read_b64_tr_b16 v[218:219], v242 offset:32768
	ds_read_b64_tr_b16 v[220:221], v242 offset:36864
	v_mfma_f32_16x16x32_bf16 v[134:137], v[186:189], v[174:177], v[134:137]
	v_add_f32_e32 v251, v113, v251
	v_cvt_pk_bf16_f32 v102, v102, v103
	s_add_u32 m0, s80, 17408
	s_nop 0
	global_load_lds_dwordx4 v249, s[100:101]
	s_waitcnt lgkmcnt(6)
; __device__ __forceinline__ void partialSM(f32x16& p0, f32x16& p1, float mC) {
;   (void)mC; (void)p1;
;   for (int r = 0; r < 16; ++r) p0[r] = __builtin_amdgcn_exp2f(p0[r]);
; }
; __device__ __forceinline__ void finishSM(f32x16& p0, f32x16& p1, float& l_reg, bf16x8& pa0, bf16x8& pa1, bf16x8& pa2, bf16x8& pa3) {
;   for (int r = 0; r < 16; ++r) p1[r] = __builtin_amdgcn_exp2f(p1[r]);
;   float ps = 0; for (int r = 0; r < 16; ++r) ps += p0[r]; for (int r = 0; r < 16; ++r) ps += p1[r];
;   { auto rr = __builtin_amdgcn_permlane32_swap(__float_as_uint(ps), __float_as_uint(ps), false, false);
;     ps = __uint_as_float(rr[0]) + __uint_as_float(rr[1]); }
;   l_reg += ps;
;     ...
;   PK4(p0, 0, pa0); PK4(p0, 8, pa1); PK4(p1, 0, pa2); PK4(p1, 8, pa3);
;     ...
; }
; __device__ __forceinline__ void qkt(f32x16& p0, f32x16& p1, const bf16* Ks, const bf16x8* qr, int r32, int hi, const f32x16& negm) {
; #pragma unroll
;   for (int d0 = 0; d0 < 8; ++d0) { int cb = (d0 * 16 + hi * 8) * 2;
;     bf16x8 b0 = *reinterpret_cast<const bf16x8*>((const char*)Ks + KSWZ(r32, cb));
;     bf16x8 b1 = *reinterpret_cast<const bf16x8*>((const char*)Ks + KSWZ(32 + r32, cb));
;     if (d0 == 0) { p0 = __builtin_amdgcn_mfma_f32_32x32x16_bf16(b0, qr[0], negm, 0, 0, 0); p1 = __builtin_amdgcn_mfma_f32_32x32x16_bf16(b1, qr[0], negm, 0, 0, 0); }
;     else { p0 = __builtin_amdgcn_mfma_f32_32x32x16_bf16(b0, qr[d0], p0, 0, 0, 0); p1 = __builtin_amdgcn_mfma_f32_32x32x16_bf16(b1, qr[d0], p1, 0, 0, 0); } }
; }
; __device__ __forceinline__ int v_st(int k, int c) { const int kk = (k & ~0xC) | ((k & 4) << 1) | ((k & 8) >> 1); return ((kk >> 3) * 4 + (c >> 5)) * 512 + ((kk & 7) * 32 + (c & 31)) * 2; }
; __device__ __forceinline__ int v_rd_base(int lane) { return ((lane & 3) << 3) | (((lane >> 2) & 3) << 6) | (((lane >> 4) & 1) << 5) | (((lane >> 5) & 1) << 8); }
; template <int OFF> __device__ __forceinline__ s16x4 tr_read(int vb) {
;   s16x4 r; asm volatile("ds_read_b64_tr_b16 %0, %1 offset:%2" : "=&v"(r) : "v"(vb), "i"(OFF) : "memory"); return r;
; }
; template <int D0> __device__ __forceinline__ void pv_one(f32x16& od, int vb, bf16x8 pa0, bf16x8 pa1, bf16x8 pa2, bf16x8 pa3) {
;   const s16x4 l0 = tr_read<v_rd_off(D0, 0, 0)>(vb), h0 = tr_read<v_rd_off(D0, 0, 1)>(vb), l1 = tr_read<v_rd_off(D0, 1, 0)>(vb), h1 = tr_read<v_rd_off(D0, 1, 1)>(vb);
	v_mfma_f32_16x16x32_bf16 v[138:141], v[190:193], v[158:161], v[138:141]
	v_cvt_pk_bf16_f32 v103, v104, v105
	ds_read_b64_tr_b16 v[222:223], v243 offset:32768
	ds_read_b64_tr_b16 v[224:225], v243 offset:36864
	v_mfma_f32_16x16x32_bf16 v[142:145], v[190:193], v[174:177], v[142:145]
	v_cvt_pk_bf16_f32 v104, v110, v111
	v_cvt_pk_bf16_f32 v105, v112, v113
	v_mfma_f32_16x16x32_bf16 v[18:21], v[202:205], v[82:85], v[18:21]
	v_exp_f32_e32 v114, v114
	v_mfma_f32_16x16x32_bf16 v[22:25], v[202:205], v[86:89], v[22:25]
	ds_read_b64_tr_b16 v[202:203], v244 offset:32768
	ds_read_b64_tr_b16 v[204:205], v244 offset:36864
	v_exp_f32_e32 v115, v115
	v_mfma_f32_16x16x32_bf16 v[26:29], v[206:209], v[82:85], v[26:29]
	v_exp_f32_e32 v116, v116
	v_mfma_f32_16x16x32_bf16 v[30:33], v[206:209], v[86:89], v[30:33]
	ds_read_b64_tr_b16 v[206:207], v245 offset:32768
	ds_read_b64_tr_b16 v[208:209], v245 offset:36864
	v_exp_f32_e32 v117, v117
	s_waitcnt lgkmcnt(10)
	v_mfma_f32_16x16x32_bf16 v[34:37], v[210:213], v[82:85], v[34:37]
	v_exp_f32_e32 v118, v118
	v_mfma_f32_16x16x32_bf16 v[38:41], v[210:213], v[86:89], v[38:41]
	ds_read_b64_tr_b16 v[210:211], v238 offset:40960
	ds_read_b64_tr_b16 v[212:213], v238 offset:45056
	v_exp_f32_e32 v119, v119
	s_waitcnt lgkmcnt(10)
	v_mfma_f32_16x16x32_bf16 v[42:45], v[214:217], v[82:85], v[42:45]
	v_exp_f32_e32 v120, v120
	v_mfma_f32_16x16x32_bf16 v[46:49], v[214:217], v[86:89], v[46:49]
	ds_read_b64_tr_b16 v[214:215], v239 offset:40960
	ds_read_b64_tr_b16 v[216:217], v239 offset:45056
	v_exp_f32_e32 v121, v121
	s_waitcnt lgkmcnt(10)
	v_mfma_f32_16x16x32_bf16 v[50:53], v[218:221], v[82:85], v[50:53]
	v_exp_f32_e32 v122, v122
	v_mfma_f32_16x16x32_bf16 v[54:57], v[218:221], v[86:89], v[54:57]
	ds_read_b64_tr_b16 v[218:219], v240 offset:40960
	ds_read_b64_tr_b16 v[220:221], v240 offset:45056
	v_exp_f32_e32 v123, v123
	s_waitcnt lgkmcnt(10)
	v_mfma_f32_16x16x32_bf16 v[58:61], v[222:225], v[82:85], v[58:61]
	v_exp_f32_e32 v124, v124
	v_mfma_f32_16x16x32_bf16 v[62:65], v[222:225], v[86:89], v[62:65]
	ds_read_b64_tr_b16 v[222:223], v241 offset:40960
	ds_read_b64_tr_b16 v[224:225], v241 offset:45056
	v_exp_f32_e32 v125, v125
	s_waitcnt lgkmcnt(10)
	v_mfma_f32_16x16x32_bf16 v[66:69], v[202:205], v[82:85], v[66:69]
	v_exp_f32_e32 v126, v126
	v_mfma_f32_16x16x32_bf16 v[70:73], v[202:205], v[86:89], v[70:73]
	ds_read_b64_tr_b16 v[202:203], v242 offset:40960
	ds_read_b64_tr_b16 v[204:205], v242 offset:45056
	v_exp_f32_e32 v127, v127
	s_waitcnt lgkmcnt(10)
	v_mfma_f32_16x16x32_bf16 v[74:77], v[206:209], v[82:85], v[74:77]
	v_exp_f32_e32 v128, v128
	v_mfma_f32_16x16x32_bf16 v[78:81], v[206:209], v[86:89], v[78:81]
	ds_read_b64_tr_b16 v[206:207], v243 offset:40960
	ds_read_b64_tr_b16 v[208:209], v243 offset:45056
	v_exp_f32_e32 v129, v129
	s_waitcnt lgkmcnt(10)
	v_mfma_f32_16x16x32_bf16 v[18:21], v[210:213], v[98:101], v[18:21]
	v_exp_f32_e32 v130, v130
	v_mfma_f32_16x16x32_bf16 v[22:25], v[210:213], v[102:105], v[22:25]
	ds_read_b64_tr_b16 v[210:211], v244 offset:40960
	ds_read_b64_tr_b16 v[212:213], v244 offset:45056
	v_exp_f32_e32 v131, v131
	s_waitcnt lgkmcnt(10)
	v_mfma_f32_16x16x32_bf16 v[26:29], v[214:217], v[98:101], v[26:29]
	v_exp_f32_e32 v132, v132
	v_mfma_f32_16x16x32_bf16 v[30:33], v[214:217], v[102:105], v[30:33]
	ds_read_b64_tr_b16 v[214:215], v245 offset:40960
	ds_read_b64_tr_b16 v[216:217], v245 offset:45056
	v_exp_f32_e32 v133, v133
	s_waitcnt lgkmcnt(10)
	v_mfma_f32_16x16x32_bf16 v[34:37], v[218:221], v[98:101], v[34:37]
	v_exp_f32_e32 v134, v134
	v_mfma_f32_16x16x32_bf16 v[38:41], v[218:221], v[102:105], v[38:41]
	v_exp_f32_e32 v135, v135
	s_waitcnt lgkmcnt(8)
	v_mfma_f32_16x16x32_bf16 v[42:45], v[222:225], v[98:101], v[42:45]
	v_exp_f32_e32 v136, v136
	v_mfma_f32_16x16x32_bf16 v[46:49], v[222:225], v[102:105], v[46:49]
	v_exp_f32_e32 v137, v137
	s_waitcnt lgkmcnt(6)
	v_mfma_f32_16x16x32_bf16 v[50:53], v[202:205], v[98:101], v[50:53]
	v_exp_f32_e32 v138, v138
	ds_read_b128 v[178:181], v234 offset:0
	v_mfma_f32_16x16x32_bf16 v[54:57], v[202:205], v[102:105], v[54:57]
	v_exp_f32_e32 v139, v139
	s_waitcnt lgkmcnt(5)
	v_mfma_f32_16x16x32_bf16 v[58:61], v[206:209], v[98:101], v[58:61]
	v_exp_f32_e32 v140, v140
	ds_read_b128 v[182:185], v234 offset:4096
	v_mfma_f32_16x16x32_bf16 v[62:65], v[206:209], v[102:105], v[62:65]
	v_exp_f32_e32 v141, v141
	s_waitcnt lgkmcnt(4)
	v_mfma_f32_16x16x32_bf16 v[66:69], v[210:213], v[98:101], v[66:69]
	v_exp_f32_e32 v142, v142
	ds_read_b128 v[186:189], v234 offset:8192
	v_mfma_f32_16x16x32_bf16 v[70:73], v[210:213], v[102:105], v[70:73]
	v_exp_f32_e32 v143, v143
	s_waitcnt lgkmcnt(3)
	v_mfma_f32_16x16x32_bf16 v[74:77], v[214:217], v[98:101], v[74:77]
	v_exp_f32_e32 v144, v144
	ds_read_b128 v[190:193], v234 offset:12288
	v_mfma_f32_16x16x32_bf16 v[78:81], v[214:217], v[102:105], v[78:81]
	v_exp_f32_e32 v145, v145
	s_waitcnt vmcnt(4)
	s_barrier
; __device__ __forceinline__ void partialSM(f32x16& p0, f32x16& p1, float mC) {
;   (void)mC; (void)p1;
;   for (int r = 0; r < 16; ++r) p0[r] = __builtin_amdgcn_exp2f(p0[r]);
; }
; __device__ __forceinline__ void finishSM(f32x16& p0, f32x16& p1, float& l_reg, bf16x8& pa0, bf16x8& pa1, bf16x8& pa2, bf16x8& pa3) {
;   for (int r = 0; r < 16; ++r) p1[r] = __builtin_amdgcn_exp2f(p1[r]);
;   float ps = 0; for (int r = 0; r < 16; ++r) ps += p0[r]; for (int r = 0; r < 16; ++r) ps += p1[r];
;   { auto rr = __builtin_amdgcn_permlane32_swap(__float_as_uint(ps), __float_as_uint(ps), false, false);
;     ps = __uint_as_float(rr[0]) + __uint_as_float(rr[1]); }
;   l_reg += ps;
;     ...
;   PK4(p0, 0, pa0); PK4(p0, 8, pa1); PK4(p1, 0, pa2); PK4(p1, 8, pa3);
;     ...
; }
; __device__ __forceinline__ void qkt(f32x16& p0, f32x16& p1, const bf16* Ks, const bf16x8* qr, int r32, int hi, const f32x16& negm) {
; #pragma unroll
;   for (int d0 = 0; d0 < 8; ++d0) { int cb = (d0 * 16 + hi * 8) * 2;
;     bf16x8 b0 = *reinterpret_cast<const bf16x8*>((const char*)Ks + KSWZ(r32, cb));
;     bf16x8 b1 = *reinterpret_cast<const bf16x8*>((const char*)Ks + KSWZ(32 + r32, cb));
;     if (d0 == 0) { p0 = __builtin_amdgcn_mfma_f32_32x32x16_bf16(b0, qr[0], negm, 0, 0, 0); p1 = __builtin_amdgcn_mfma_f32_32x32x16_bf16(b1, qr[0], negm, 0, 0, 0); }
;     else { p0 = __builtin_amdgcn_mfma_f32_32x32x16_bf16(b0, qr[d0], p0, 0, 0, 0); p1 = __builtin_amdgcn_mfma_f32_32x32x16_bf16(b1, qr[d0], p1, 0, 0, 0); } }
; }
; __device__ __forceinline__ int v_st(int k, int c) { const int kk = (k & ~0xC) | ((k & 4) << 1) | ((k & 8) >> 1); return ((kk >> 3) * 4 + (c >> 5)) * 512 + ((kk & 7) * 32 + (c & 31)) * 2; }
; __device__ __forceinline__ int v_rd_base(int lane) { return ((lane & 3) << 3) | (((lane >> 2) & 3) << 6) | (((lane >> 4) & 1) << 5) | (((lane >> 5) & 1) << 8); }
; template <int OFF> __device__ __forceinline__ s16x4 tr_read(int vb) {
;   s16x4 r; asm volatile("ds_read_b64_tr_b16 %0, %1 offset:%2" : "=&v"(r) : "v"(vb), "i"(OFF) : "memory"); return r;
; }
; template <int D0> __device__ __forceinline__ void pv_one(f32x16& od, int vb, bf16x8 pa0, bf16x8 pa1, bf16x8 pa2, bf16x8 pa3) {
;   const s16x4 l0 = tr_read<v_rd_off(D0, 0, 0)>(vb), h0 = tr_read<v_rd_off(D0, 0, 1)>(vb), l1 = tr_read<v_rd_off(D0, 1, 0)>(vb), h1 = tr_read<v_rd_off(D0, 1, 1)>(vb);
	s_waitcnt lgkmcnt(3)
	v_mfma_f32_16x16x32_bf16 v[82:85], v[178:181], v[146:149], v[2:5]
	v_add_f32_e32 v250, v114, v250
	s_add_u32 s98, s98, 0x8000
	s_addc_u32 s99, s99, 0
	s_add_u32 s100, s100, 0x8000
	s_addc_u32 s101, s101, 0
	v_mfma_f32_16x16x32_bf16 v[86:89], v[178:181], v[162:165], v[2:5]
	ds_read_b128 v[178:181], v235 offset:0
	v_add_f32_e32 v250, v115, v250
	v_add_f32_e32 v250, v116, v250
	s_waitcnt lgkmcnt(3)
	v_mfma_f32_16x16x32_bf16 v[90:93], v[182:185], v[146:149], v[2:5]
	v_add_f32_e32 v250, v117, v250
	v_mfma_f32_16x16x32_bf16 v[94:97], v[182:185], v[162:165], v[2:5]
	ds_read_b128 v[182:185], v235 offset:4096
	v_add_f32_e32 v250, v122, v250
	v_add_f32_e32 v250, v123, v250
	s_waitcnt lgkmcnt(3)
	v_mfma_f32_16x16x32_bf16 v[98:101], v[186:189], v[146:149], v[2:5]
	v_add_f32_e32 v250, v124, v250
	v_mfma_f32_16x16x32_bf16 v[102:105], v[186:189], v[162:165], v[2:5]
	ds_read_b128 v[186:189], v235 offset:8192
	v_add_f32_e32 v250, v125, v250
	v_cvt_pk_bf16_f32 v114, v114, v115
	s_add_u32 m0, s79, 49152
	s_nop 0
	global_load_lds_dwordx4 v246, s[98:99]
	s_waitcnt lgkmcnt(3)
	v_mfma_f32_16x16x32_bf16 v[106:109], v[190:193], v[146:149], v[2:5]
	v_cvt_pk_bf16_f32 v115, v116, v117
	v_mfma_f32_16x16x32_bf16 v[110:113], v[190:193], v[162:165], v[2:5]
	ds_read_b128 v[190:193], v235 offset:12288
	v_cvt_pk_bf16_f32 v116, v122, v123
	v_cvt_pk_bf16_f32 v117, v124, v125
	s_waitcnt lgkmcnt(3)
	v_mfma_f32_16x16x32_bf16 v[82:85], v[178:181], v[150:153], v[82:85]
	v_add_f32_e32 v251, v118, v251
	v_mfma_f32_16x16x32_bf16 v[86:89], v[178:181], v[166:169], v[86:89]
	ds_read_b128 v[178:181], v236 offset:0
	v_add_f32_e32 v251, v119, v251
	v_add_f32_e32 v251, v120, v251
	s_waitcnt lgkmcnt(3)
	v_mfma_f32_16x16x32_bf16 v[90:93], v[182:185], v[150:153], v[90:93]
	v_add_f32_e32 v251, v121, v251
	v_mfma_f32_16x16x32_bf16 v[94:97], v[182:185], v[166:169], v[94:97]
	ds_read_b128 v[182:185], v236 offset:4096
	v_add_f32_e32 v251, v126, v251
	v_add_f32_e32 v251, v127, v251
	s_waitcnt lgkmcnt(3)
	v_mfma_f32_16x16x32_bf16 v[98:101], v[186:189], v[150:153], v[98:101]
	v_add_f32_e32 v251, v128, v251
	v_mfma_f32_16x16x32_bf16 v[102:105], v[186:189], v[166:169], v[102:105]
	ds_read_b128 v[186:189], v236 offset:8192
	v_add_f32_e32 v251, v129, v251
	v_cvt_pk_bf16_f32 v118, v118, v119
	s_add_u32 m0, s79, 50176
	s_nop 0
	global_load_lds_dwordx4 v247, s[98:99]
	s_waitcnt lgkmcnt(3)
	v_mfma_f32_16x16x32_bf16 v[106:109], v[190:193], v[150:153], v[106:109]
	v_cvt_pk_bf16_f32 v119, v120, v121
	v_mfma_f32_16x16x32_bf16 v[110:113], v[190:193], v[166:169], v[110:113]
	ds_read_b128 v[190:193], v236 offset:12288
	v_cvt_pk_bf16_f32 v120, v126, v127
	v_cvt_pk_bf16_f32 v121, v128, v129
	s_waitcnt lgkmcnt(3)
	v_mfma_f32_16x16x32_bf16 v[82:85], v[178:181], v[154:157], v[82:85]
	v_add_f32_e32 v250, v130, v250
	v_mfma_f32_16x16x32_bf16 v[86:89], v[178:181], v[170:173], v[86:89]
	ds_read_b128 v[178:181], v237 offset:0
	v_add_f32_e32 v250, v131, v250
	v_add_f32_e32 v250, v132, v250
	s_waitcnt lgkmcnt(3)
	v_mfma_f32_16x16x32_bf16 v[90:93], v[182:185], v[154:157], v[90:93]
	v_add_f32_e32 v250, v133, v250
	v_mfma_f32_16x16x32_bf16 v[94:97], v[182:185], v[170:173], v[94:97]
	ds_read_b128 v[182:185], v237 offset:4096
	v_add_f32_e32 v250, v138, v250
	v_add_f32_e32 v250, v139, v250
	s_waitcnt lgkmcnt(3)
	v_mfma_f32_16x16x32_bf16 v[98:101], v[186:189], v[154:157], v[98:101]
	v_add_f32_e32 v250, v140, v250
	ds_read_b64_tr_b16 v[202:203], v238 offset:49152
	ds_read_b64_tr_b16 v[204:205], v238 offset:53248
	v_mfma_f32_16x16x32_bf16 v[102:105], v[186:189], v[170:173], v[102:105]
	ds_read_b128 v[186:189], v237 offset:8192
	v_add_f32_e32 v250, v141, v250
	v_cvt_pk_bf16_f32 v130, v130, v131
	s_add_u32 m0, s80, 32768
	s_nop 0
	global_load_lds_dwordx4 v248, s[100:101]
	s_waitcnt lgkmcnt(5)
	v_mfma_f32_16x16x32_bf16 v[106:109], v[190:193], v[154:157], v[106:109]
	v_cvt_pk_bf16_f32 v131, v132, v133
	ds_read_b64_tr_b16 v[206:207], v239 offset:49152
	ds_read_b64_tr_b16 v[208:209], v239 offset:53248
	v_mfma_f32_16x16x32_bf16 v[110:113], v[190:193], v[170:173], v[110:113]
	ds_read_b128 v[190:193], v237 offset:12288
	v_cvt_pk_bf16_f32 v132, v138, v139
	v_cvt_pk_bf16_f32 v133, v140, v141
	s_waitcnt lgkmcnt(7)
	v_mfma_f32_16x16x32_bf16 v[82:85], v[178:181], v[158:161], v[82:85]
	v_add_f32_e32 v251, v134, v251
	ds_read_b64_tr_b16 v[210:211], v240 offset:49152
	ds_read_b64_tr_b16 v[212:213], v240 offset:53248
	v_mfma_f32_16x16x32_bf16 v[86:89], v[178:181], v[174:177], v[86:89]
	v_add_f32_e32 v251, v135, v251
	v_add_f32_e32 v251, v136, v251
	s_waitcnt lgkmcnt(8)
	v_mfma_f32_16x16x32_bf16 v[90:93], v[182:185], v[158:161], v[90:93]
	v_add_f32_e32 v251, v137, v251
	ds_read_b64_tr_b16 v[214:215], v241 offset:49152
	ds_read_b64_tr_b16 v[216:217], v241 offset:53248
	v_mfma_f32_16x16x32_bf16 v[94:97], v[182:185], v[174:177], v[94:97]
	v_add_f32_e32 v251, v142, v251
	v_add_f32_e32 v251, v143, v251
	s_waitcnt lgkmcnt(7)
	v_mfma_f32_16x16x32_bf16 v[98:101], v[186:189], v[158:161], v[98:101]
	v_add_f32_e32 v251, v144, v251
	ds_read_b64_tr_b16 v[218:219], v242 offset:49152
	ds_read_b64_tr_b16 v[220:221], v242 offset:53248
	v_mfma_f32_16x16x32_bf16 v[102:105], v[186:189], v[174:177], v[102:105]
	v_add_f32_e32 v251, v145, v251
	v_cvt_pk_bf16_f32 v134, v134, v135
	s_add_u32 m0, s80, 33792
	s_nop 0
	global_load_lds_dwordx4 v249, s[100:101]
	s_waitcnt lgkmcnt(6)
; __device__ __forceinline__ void partialSM(f32x16& p0, f32x16& p1, float mC) {
;   (void)mC; (void)p1;
;   for (int r = 0; r < 16; ++r) p0[r] = __builtin_amdgcn_exp2f(p0[r]);
; }
; __device__ __forceinline__ void finishSM(f32x16& p0, f32x16& p1, float& l_reg, bf16x8& pa0, bf16x8& pa1, bf16x8& pa2, bf16x8& pa3) {
;   for (int r = 0; r < 16; ++r) p1[r] = __builtin_amdgcn_exp2f(p1[r]);
;   float ps = 0; for (int r = 0; r < 16; ++r) ps += p0[r]; for (int r = 0; r < 16; ++r) ps += p1[r];
;   { auto rr = __builtin_amdgcn_permlane32_swap(__float_as_uint(ps), __float_as_uint(ps), false, false);
;     ps = __uint_as_float(rr[0]) + __uint_as_float(rr[1]); }
;   l_reg += ps;
;     ...
;   PK4(p0, 0, pa0); PK4(p0, 8, pa1); PK4(p1, 0, pa2); PK4(p1, 8, pa3);
;     ...
; }
; __device__ __forceinline__ void qkt(f32x16& p0, f32x16& p1, const bf16* Ks, const bf16x8* qr, int r32, int hi, const f32x16& negm) {
; #pragma unroll
;   for (int d0 = 0; d0 < 8; ++d0) { int cb = (d0 * 16 + hi * 8) * 2;
;     bf16x8 b0 = *reinterpret_cast<const bf16x8*>((const char*)Ks + KSWZ(r32, cb));
;     bf16x8 b1 = *reinterpret_cast<const bf16x8*>((const char*)Ks + KSWZ(32 + r32, cb));
;     if (d0 == 0) { p0 = __builtin_amdgcn_mfma_f32_32x32x16_bf16(b0, qr[0], negm, 0, 0, 0); p1 = __builtin_amdgcn_mfma_f32_32x32x16_bf16(b1, qr[0], negm, 0, 0, 0); }
;     else { p0 = __builtin_amdgcn_mfma_f32_32x32x16_bf16(b0, qr[d0], p0, 0, 0, 0); p1 = __builtin_amdgcn_mfma_f32_32x32x16_bf16(b1, qr[d0], p1, 0, 0, 0); } }
; }
; __device__ __forceinline__ int v_st(int k, int c) { const int kk = (k & ~0xC) | ((k & 4) << 1) | ((k & 8) >> 1); return ((kk >> 3) * 4 + (c >> 5)) * 512 + ((kk & 7) * 32 + (c & 31)) * 2; }
; __device__ __forceinline__ int v_rd_base(int lane) { return ((lane & 3) << 3) | (((lane >> 2) & 3) << 6) | (((lane >> 4) & 1) << 5) | (((lane >> 5) & 1) << 8); }
; template <int OFF> __device__ __forceinline__ s16x4 tr_read(int vb) {
;   s16x4 r; asm volatile("ds_read_b64_tr_b16 %0, %1 offset:%2" : "=&v"(r) : "v"(vb), "i"(OFF) : "memory"); return r;
; }
; template <int D0> __device__ __forceinline__ void pv_one(f32x16& od, int vb, bf16x8 pa0, bf16x8 pa1, bf16x8 pa2, bf16x8 pa3) {
;   const s16x4 l0 = tr_read<v_rd_off(D0, 0, 0)>(vb), h0 = tr_read<v_rd_off(D0, 0, 1)>(vb), l1 = tr_read<v_rd_off(D0, 1, 0)>(vb), h1 = tr_read<v_rd_off(D0, 1, 1)>(vb);
	v_mfma_f32_16x16x32_bf16 v[106:109], v[190:193], v[158:161], v[106:109]
	v_cvt_pk_bf16_f32 v135, v136, v137
	ds_read_b64_tr_b16 v[222:223], v243 offset:49152
	ds_read_b64_tr_b16 v[224:225], v243 offset:53248
	v_mfma_f32_16x16x32_bf16 v[110:113], v[190:193], v[174:177], v[110:113]
	v_cvt_pk_bf16_f32 v136, v142, v143
	v_cvt_pk_bf16_f32 v137, v144, v145
	v_mfma_f32_16x16x32_bf16 v[18:21], v[202:205], v[114:117], v[18:21]
	v_exp_f32_e32 v82, v82
	v_mfma_f32_16x16x32_bf16 v[22:25], v[202:205], v[118:121], v[22:25]
	ds_read_b64_tr_b16 v[202:203], v244 offset:49152
	ds_read_b64_tr_b16 v[204:205], v244 offset:53248
	v_exp_f32_e32 v83, v83
	v_mfma_f32_16x16x32_bf16 v[26:29], v[206:209], v[114:117], v[26:29]
	v_exp_f32_e32 v84, v84
	v_mfma_f32_16x16x32_bf16 v[30:33], v[206:209], v[118:121], v[30:33]
	ds_read_b64_tr_b16 v[206:207], v245 offset:49152
	ds_read_b64_tr_b16 v[208:209], v245 offset:53248
	v_exp_f32_e32 v85, v85
	s_waitcnt lgkmcnt(10)
	v_mfma_f32_16x16x32_bf16 v[34:37], v[210:213], v[114:117], v[34:37]
	v_exp_f32_e32 v86, v86
	v_mfma_f32_16x16x32_bf16 v[38:41], v[210:213], v[118:121], v[38:41]
	ds_read_b64_tr_b16 v[210:211], v238 offset:57344
	ds_read_b64_tr_b16 v[212:213], v238 offset:61440
	v_exp_f32_e32 v87, v87
	s_waitcnt lgkmcnt(10)
	v_mfma_f32_16x16x32_bf16 v[42:45], v[214:217], v[114:117], v[42:45]
	v_exp_f32_e32 v88, v88
	v_mfma_f32_16x16x32_bf16 v[46:49], v[214:217], v[118:121], v[46:49]
	ds_read_b64_tr_b16 v[214:215], v239 offset:57344
	ds_read_b64_tr_b16 v[216:217], v239 offset:61440
	v_exp_f32_e32 v89, v89
	s_waitcnt lgkmcnt(10)
	v_mfma_f32_16x16x32_bf16 v[50:53], v[218:221], v[114:117], v[50:53]
	v_exp_f32_e32 v90, v90
	v_mfma_f32_16x16x32_bf16 v[54:57], v[218:221], v[118:121], v[54:57]
	ds_read_b64_tr_b16 v[218:219], v240 offset:57344
	ds_read_b64_tr_b16 v[220:221], v240 offset:61440
	v_exp_f32_e32 v91, v91
	s_waitcnt lgkmcnt(10)
	v_mfma_f32_16x16x32_bf16 v[58:61], v[222:225], v[114:117], v[58:61]
	v_exp_f32_e32 v92, v92
	v_mfma_f32_16x16x32_bf16 v[62:65], v[222:225], v[118:121], v[62:65]
	ds_read_b64_tr_b16 v[222:223], v241 offset:57344
	ds_read_b64_tr_b16 v[224:225], v241 offset:61440
	v_exp_f32_e32 v93, v93
	s_waitcnt lgkmcnt(10)
	v_mfma_f32_16x16x32_bf16 v[66:69], v[202:205], v[114:117], v[66:69]
	v_exp_f32_e32 v94, v94
	v_mfma_f32_16x16x32_bf16 v[70:73], v[202:205], v[118:121], v[70:73]
	ds_read_b64_tr_b16 v[202:203], v242 offset:57344
	ds_read_b64_tr_b16 v[204:205], v242 offset:61440
	v_exp_f32_e32 v95, v95
	s_waitcnt lgkmcnt(10)
	v_mfma_f32_16x16x32_bf16 v[74:77], v[206:209], v[114:117], v[74:77]
	v_exp_f32_e32 v96, v96
	v_mfma_f32_16x16x32_bf16 v[78:81], v[206:209], v[118:121], v[78:81]
	ds_read_b64_tr_b16 v[206:207], v243 offset:57344
	ds_read_b64_tr_b16 v[208:209], v243 offset:61440
	v_exp_f32_e32 v97, v97
	s_waitcnt lgkmcnt(10)
	v_mfma_f32_16x16x32_bf16 v[18:21], v[210:213], v[130:133], v[18:21]
	v_exp_f32_e32 v98, v98
	v_mfma_f32_16x16x32_bf16 v[22:25], v[210:213], v[134:137], v[22:25]
	ds_read_b64_tr_b16 v[210:211], v244 offset:57344
	ds_read_b64_tr_b16 v[212:213], v244 offset:61440
	v_exp_f32_e32 v99, v99
	s_waitcnt lgkmcnt(10)
	v_mfma_f32_16x16x32_bf16 v[26:29], v[214:217], v[130:133], v[26:29]
	v_exp_f32_e32 v100, v100
	v_mfma_f32_16x16x32_bf16 v[30:33], v[214:217], v[134:137], v[30:33]
	ds_read_b64_tr_b16 v[214:215], v245 offset:57344
	ds_read_b64_tr_b16 v[216:217], v245 offset:61440
	v_exp_f32_e32 v101, v101
	s_waitcnt lgkmcnt(10)
	v_mfma_f32_16x16x32_bf16 v[34:37], v[218:221], v[130:133], v[34:37]
	v_exp_f32_e32 v102, v102
	v_mfma_f32_16x16x32_bf16 v[38:41], v[218:221], v[134:137], v[38:41]
	v_exp_f32_e32 v103, v103
	s_waitcnt lgkmcnt(8)
	v_mfma_f32_16x16x32_bf16 v[42:45], v[222:225], v[130:133], v[42:45]
	v_exp_f32_e32 v104, v104
	v_mfma_f32_16x16x32_bf16 v[46:49], v[222:225], v[134:137], v[46:49]
	v_exp_f32_e32 v105, v105
	s_waitcnt lgkmcnt(6)
	v_mfma_f32_16x16x32_bf16 v[50:53], v[202:205], v[130:133], v[50:53]
	v_exp_f32_e32 v106, v106
	ds_read_b128 v[178:181], v234 offset:16384
	v_mfma_f32_16x16x32_bf16 v[54:57], v[202:205], v[134:137], v[54:57]
	v_exp_f32_e32 v107, v107
	s_waitcnt lgkmcnt(5)
	v_mfma_f32_16x16x32_bf16 v[58:61], v[206:209], v[130:133], v[58:61]
	v_exp_f32_e32 v108, v108
	ds_read_b128 v[182:185], v234 offset:20480
	v_mfma_f32_16x16x32_bf16 v[62:65], v[206:209], v[134:137], v[62:65]
	v_exp_f32_e32 v109, v109
	s_waitcnt lgkmcnt(4)
	v_mfma_f32_16x16x32_bf16 v[66:69], v[210:213], v[130:133], v[66:69]
	v_exp_f32_e32 v110, v110
	ds_read_b128 v[186:189], v234 offset:24576
	v_mfma_f32_16x16x32_bf16 v[70:73], v[210:213], v[134:137], v[70:73]
	v_exp_f32_e32 v111, v111
	s_waitcnt lgkmcnt(3)
	v_mfma_f32_16x16x32_bf16 v[74:77], v[214:217], v[130:133], v[74:77]
	v_exp_f32_e32 v112, v112
	ds_read_b128 v[190:193], v234 offset:28672
	v_mfma_f32_16x16x32_bf16 v[78:81], v[214:217], v[134:137], v[78:81]
	v_exp_f32_e32 v113, v113
	s_waitcnt vmcnt(4)
	s_add_i32 s15, s15, 1
	s_cmp_lt_u32 s15, 32
	s_cbranch_scc1 .Lattn_loop
	s_barrier
; __device__ __forceinline__ void partialSM(f32x16& p0, f32x16& p1, float mC) {
;   (void)mC; (void)p1;
;   for (int r = 0; r < 16; ++r) p0[r] = __builtin_amdgcn_exp2f(p0[r]);
; }
; __device__ __forceinline__ void finishSM(f32x16& p0, f32x16& p1, float& l_reg, bf16x8& pa0, bf16x8& pa1, bf16x8& pa2, bf16x8& pa3) {
;   for (int r = 0; r < 16; ++r) p1[r] = __builtin_amdgcn_exp2f(p1[r]);
;   float ps = 0; for (int r = 0; r < 16; ++r) ps += p0[r]; for (int r = 0; r < 16; ++r) ps += p1[r];
;   { auto rr = __builtin_amdgcn_permlane32_swap(__float_as_uint(ps), __float_as_uint(ps), false, false);
;     ps = __uint_as_float(rr[0]) + __uint_as_float(rr[1]); }
;   l_reg += ps;
;     ...
;   PK4(p0, 0, pa0); PK4(p0, 8, pa1); PK4(p1, 0, pa2); PK4(p1, 8, pa3);
;     ...
; }
; __device__ __forceinline__ void qkt(f32x16& p0, f32x16& p1, const bf16* Ks, const bf16x8* qr, int r32, int hi, const f32x16& negm) {
; #pragma unroll
;   for (int d0 = 0; d0 < 8; ++d0) { int cb = (d0 * 16 + hi * 8) * 2;
;     bf16x8 b0 = *reinterpret_cast<const bf16x8*>((const char*)Ks + KSWZ(r32, cb));
;     bf16x8 b1 = *reinterpret_cast<const bf16x8*>((const char*)Ks + KSWZ(32 + r32, cb));
;     if (d0 == 0) { p0 = __builtin_amdgcn_mfma_f32_32x32x16_bf16(b0, qr[0], negm, 0, 0, 0); p1 = __builtin_amdgcn_mfma_f32_32x32x16_bf16(b1, qr[0], negm, 0, 0, 0); }
;     else { p0 = __builtin_amdgcn_mfma_f32_32x32x16_bf16(b0, qr[d0], p0, 0, 0, 0); p1 = __builtin_amdgcn_mfma_f32_32x32x16_bf16(b1, qr[d0], p1, 0, 0, 0); } }
; }
; __device__ __forceinline__ int v_st(int k, int c) { const int kk = (k & ~0xC) | ((k & 4) << 1) | ((k & 8) >> 1); return ((kk >> 3) * 4 + (c >> 5)) * 512 + ((kk & 7) * 32 + (c & 31)) * 2; }
; __device__ __forceinline__ int v_rd_base(int lane) { return ((lane & 3) << 3) | (((lane >> 2) & 3) << 6) | (((lane >> 4) & 1) << 5) | (((lane >> 5) & 1) << 8); }
; template <int OFF> __device__ __forceinline__ s16x4 tr_read(int vb) {
;   s16x4 r; asm volatile("ds_read_b64_tr_b16 %0, %1 offset:%2" : "=&v"(r) : "v"(vb), "i"(OFF) : "memory"); return r;
; }
; template <int D0> __device__ __forceinline__ void pv_one(f32x16& od, int vb, bf16x8 pa0, bf16x8 pa1, bf16x8 pa2, bf16x8 pa3) {
;   const s16x4 l0 = tr_read<v_rd_off(D0, 0, 0)>(vb), h0 = tr_read<v_rd_off(D0, 0, 1)>(vb), l1 = tr_read<v_rd_off(D0, 1, 0)>(vb), h1 = tr_read<v_rd_off(D0, 1, 1)>(vb);
	s_waitcnt lgkmcnt(3)
	v_mfma_f32_16x16x32_bf16 v[114:117], v[178:181], v[146:149], v[2:5]
	v_add_f32_e32 v250, v82, v250
	s_add_u32 s98, s98, 0x8000
	s_addc_u32 s99, s99, 0
	s_add_u32 s100, s100, 0x8000
	s_addc_u32 s101, s101, 0
	v_mfma_f32_16x16x32_bf16 v[118:121], v[178:181], v[162:165], v[2:5]
	ds_read_b128 v[178:181], v235 offset:16384
	v_add_f32_e32 v250, v83, v250
	v_add_f32_e32 v250, v84, v250
	s_waitcnt lgkmcnt(3)
	v_mfma_f32_16x16x32_bf16 v[122:125], v[182:185], v[146:149], v[2:5]
	v_add_f32_e32 v250, v85, v250
	v_mfma_f32_16x16x32_bf16 v[126:129], v[182:185], v[162:165], v[2:5]
	ds_read_b128 v[182:185], v235 offset:20480
	v_add_f32_e32 v250, v90, v250
	v_add_f32_e32 v250, v91, v250
	s_waitcnt lgkmcnt(3)
	v_mfma_f32_16x16x32_bf16 v[130:133], v[186:189], v[146:149], v[2:5]
	v_add_f32_e32 v250, v92, v250
	v_mfma_f32_16x16x32_bf16 v[134:137], v[186:189], v[162:165], v[2:5]
	ds_read_b128 v[186:189], v235 offset:24576
	v_add_f32_e32 v250, v93, v250
	v_cvt_pk_bf16_f32 v82, v82, v83
	s_add_u32 m0, s80, 49152
	s_nop 0
	global_load_lds_dwordx4 v248, s[100:101]
	s_waitcnt lgkmcnt(3)
	v_mfma_f32_16x16x32_bf16 v[138:141], v[190:193], v[146:149], v[2:5]
	v_cvt_pk_bf16_f32 v83, v84, v85
	v_mfma_f32_16x16x32_bf16 v[142:145], v[190:193], v[162:165], v[2:5]
	ds_read_b128 v[190:193], v235 offset:28672
	v_cvt_pk_bf16_f32 v84, v90, v91
	v_cvt_pk_bf16_f32 v85, v92, v93
	s_waitcnt lgkmcnt(3)
	v_mfma_f32_16x16x32_bf16 v[114:117], v[178:181], v[150:153], v[114:117]
	v_add_f32_e32 v251, v86, v251
	v_mfma_f32_16x16x32_bf16 v[118:121], v[178:181], v[166:169], v[118:121]
	ds_read_b128 v[178:181], v236 offset:16384
	v_add_f32_e32 v251, v87, v251
	v_add_f32_e32 v251, v88, v251
	s_waitcnt lgkmcnt(3)
	v_mfma_f32_16x16x32_bf16 v[122:125], v[182:185], v[150:153], v[122:125]
	v_add_f32_e32 v251, v89, v251
	v_mfma_f32_16x16x32_bf16 v[126:129], v[182:185], v[166:169], v[126:129]
	ds_read_b128 v[182:185], v236 offset:20480
	v_add_f32_e32 v251, v94, v251
	v_add_f32_e32 v251, v95, v251
	s_waitcnt lgkmcnt(3)
	v_mfma_f32_16x16x32_bf16 v[130:133], v[186:189], v[150:153], v[130:133]
	v_add_f32_e32 v251, v96, v251
	v_mfma_f32_16x16x32_bf16 v[134:137], v[186:189], v[166:169], v[134:137]
	ds_read_b128 v[186:189], v236 offset:24576
	v_add_f32_e32 v251, v97, v251
	v_cvt_pk_bf16_f32 v86, v86, v87
	s_add_u32 m0, s80, 50176
	s_nop 0
	global_load_lds_dwordx4 v249, s[100:101]
	s_waitcnt lgkmcnt(3)
	v_mfma_f32_16x16x32_bf16 v[138:141], v[190:193], v[150:153], v[138:141]
	v_cvt_pk_bf16_f32 v87, v88, v89
	v_mfma_f32_16x16x32_bf16 v[142:145], v[190:193], v[166:169], v[142:145]
	ds_read_b128 v[190:193], v236 offset:28672
	v_cvt_pk_bf16_f32 v88, v94, v95
	v_cvt_pk_bf16_f32 v89, v96, v97
	s_waitcnt lgkmcnt(3)
	v_mfma_f32_16x16x32_bf16 v[114:117], v[178:181], v[154:157], v[114:117]
	v_add_f32_e32 v250, v98, v250
	v_mfma_f32_16x16x32_bf16 v[118:121], v[178:181], v[170:173], v[118:121]
	ds_read_b128 v[178:181], v237 offset:16384
	v_add_f32_e32 v250, v99, v250
	v_add_f32_e32 v250, v100, v250
	s_waitcnt lgkmcnt(3)
	v_mfma_f32_16x16x32_bf16 v[122:125], v[182:185], v[154:157], v[122:125]
	v_add_f32_e32 v250, v101, v250
	v_mfma_f32_16x16x32_bf16 v[126:129], v[182:185], v[170:173], v[126:129]
	ds_read_b128 v[182:185], v237 offset:20480
	v_add_f32_e32 v250, v106, v250
	v_add_f32_e32 v250, v107, v250
	s_waitcnt lgkmcnt(3)
	v_mfma_f32_16x16x32_bf16 v[130:133], v[186:189], v[154:157], v[130:133]
	v_add_f32_e32 v250, v108, v250
	ds_read_b64_tr_b16 v[202:203], v238 offset:0
	ds_read_b64_tr_b16 v[204:205], v238 offset:4096
	v_mfma_f32_16x16x32_bf16 v[134:137], v[186:189], v[170:173], v[134:137]
	ds_read_b128 v[186:189], v237 offset:24576
	v_add_f32_e32 v250, v109, v250
	v_cvt_pk_bf16_f32 v98, v98, v99
	s_waitcnt lgkmcnt(5)
	v_mfma_f32_16x16x32_bf16 v[138:141], v[190:193], v[154:157], v[138:141]
	v_cvt_pk_bf16_f32 v99, v100, v101
	ds_read_b64_tr_b16 v[206:207], v239 offset:0
	ds_read_b64_tr_b16 v[208:209], v239 offset:4096
	v_mfma_f32_16x16x32_bf16 v[142:145], v[190:193], v[170:173], v[142:145]
	ds_read_b128 v[190:193], v237 offset:28672
	v_cvt_pk_bf16_f32 v100, v106, v107
	v_cvt_pk_bf16_f32 v101, v108, v109
	s_waitcnt lgkmcnt(7)
	v_mfma_f32_16x16x32_bf16 v[114:117], v[178:181], v[158:161], v[114:117]
	v_add_f32_e32 v251, v102, v251
	ds_read_b64_tr_b16 v[210:211], v240 offset:0
	ds_read_b64_tr_b16 v[212:213], v240 offset:4096
	v_mfma_f32_16x16x32_bf16 v[118:121], v[178:181], v[174:177], v[118:121]
	v_add_f32_e32 v251, v103, v251
	v_add_f32_e32 v251, v104, v251
	s_waitcnt lgkmcnt(8)
	v_mfma_f32_16x16x32_bf16 v[122:125], v[182:185], v[158:161], v[122:125]
	v_add_f32_e32 v251, v105, v251
	ds_read_b64_tr_b16 v[214:215], v241 offset:0
	ds_read_b64_tr_b16 v[216:217], v241 offset:4096
	v_mfma_f32_16x16x32_bf16 v[126:129], v[182:185], v[174:177], v[126:129]
	v_add_f32_e32 v251, v110, v251
	v_add_f32_e32 v251, v111, v251
	s_waitcnt lgkmcnt(7)
	v_mfma_f32_16x16x32_bf16 v[130:133], v[186:189], v[158:161], v[130:133]
	v_add_f32_e32 v251, v112, v251
	ds_read_b64_tr_b16 v[218:219], v242 offset:0
	ds_read_b64_tr_b16 v[220:221], v242 offset:4096
	v_mfma_f32_16x16x32_bf16 v[134:137], v[186:189], v[174:177], v[134:137]
	v_add_f32_e32 v251, v113, v251
	v_cvt_pk_bf16_f32 v102, v102, v103
	s_waitcnt lgkmcnt(6)
; __device__ __forceinline__ void partialSM(f32x16& p0, f32x16& p1, float mC) {
;   (void)mC; (void)p1;
;   for (int r = 0; r < 16; ++r) p0[r] = __builtin_amdgcn_exp2f(p0[r]);
; }
; __device__ __forceinline__ void finishSM(f32x16& p0, f32x16& p1, float& l_reg, bf16x8& pa0, bf16x8& pa1, bf16x8& pa2, bf16x8& pa3) {
;   for (int r = 0; r < 16; ++r) p1[r] = __builtin_amdgcn_exp2f(p1[r]);
;   float ps = 0; for (int r = 0; r < 16; ++r) ps += p0[r]; for (int r = 0; r < 16; ++r) ps += p1[r];
;   { auto rr = __builtin_amdgcn_permlane32_swap(__float_as_uint(ps), __float_as_uint(ps), false, false);
;     ps = __uint_as_float(rr[0]) + __uint_as_float(rr[1]); }
;   l_reg += ps;
;     ...
;   PK4(p0, 0, pa0); PK4(p0, 8, pa1); PK4(p1, 0, pa2); PK4(p1, 8, pa3);
;     ...
; }
; __device__ __forceinline__ void qkt(f32x16& p0, f32x16& p1, const bf16* Ks, const bf16x8* qr, int r32, int hi, const f32x16& negm) {
; #pragma unroll
;   for (int d0 = 0; d0 < 8; ++d0) { int cb = (d0 * 16 + hi * 8) * 2;
;     bf16x8 b0 = *reinterpret_cast<const bf16x8*>((const char*)Ks + KSWZ(r32, cb));
;     bf16x8 b1 = *reinterpret_cast<const bf16x8*>((const char*)Ks + KSWZ(32 + r32, cb));
;     if (d0 == 0) { p0 = __builtin_amdgcn_mfma_f32_32x32x16_bf16(b0, qr[0], negm, 0, 0, 0); p1 = __builtin_amdgcn_mfma_f32_32x32x16_bf16(b1, qr[0], negm, 0, 0, 0); }
;     else { p0 = __builtin_amdgcn_mfma_f32_32x32x16_bf16(b0, qr[d0], p0, 0, 0, 0); p1 = __builtin_amdgcn_mfma_f32_32x32x16_bf16(b1, qr[d0], p1, 0, 0, 0); } }
; }
; __device__ __forceinline__ int v_st(int k, int c) { const int kk = (k & ~0xC) | ((k & 4) << 1) | ((k & 8) >> 1); return ((kk >> 3) * 4 + (c >> 5)) * 512 + ((kk & 7) * 32 + (c & 31)) * 2; }
; __device__ __forceinline__ int v_rd_base(int lane) { return ((lane & 3) << 3) | (((lane >> 2) & 3) << 6) | (((lane >> 4) & 1) << 5) | (((lane >> 5) & 1) << 8); }
; template <int OFF> __device__ __forceinline__ s16x4 tr_read(int vb) {
;   s16x4 r; asm volatile("ds_read_b64_tr_b16 %0, %1 offset:%2" : "=&v"(r) : "v"(vb), "i"(OFF) : "memory"); return r;
; }
; template <int D0> __device__ __forceinline__ void pv_one(f32x16& od, int vb, bf16x8 pa0, bf16x8 pa1, bf16x8 pa2, bf16x8 pa3) {
;   const s16x4 l0 = tr_read<v_rd_off(D0, 0, 0)>(vb), h0 = tr_read<v_rd_off(D0, 0, 1)>(vb), l1 = tr_read<v_rd_off(D0, 1, 0)>(vb), h1 = tr_read<v_rd_off(D0, 1, 1)>(vb);
	v_mfma_f32_16x16x32_bf16 v[138:141], v[190:193], v[158:161], v[138:141]
	v_cvt_pk_bf16_f32 v103, v104, v105
	ds_read_b64_tr_b16 v[222:223], v243 offset:0
	ds_read_b64_tr_b16 v[224:225], v243 offset:4096
	v_mfma_f32_16x16x32_bf16 v[142:145], v[190:193], v[174:177], v[142:145]
	v_cvt_pk_bf16_f32 v104, v110, v111
	v_cvt_pk_bf16_f32 v105, v112, v113
	v_mfma_f32_16x16x32_bf16 v[18:21], v[202:205], v[82:85], v[18:21]
	v_exp_f32_e32 v114, v114
	v_mfma_f32_16x16x32_bf16 v[22:25], v[202:205], v[86:89], v[22:25]
	ds_read_b64_tr_b16 v[202:203], v244 offset:0
	ds_read_b64_tr_b16 v[204:205], v244 offset:4096
	v_exp_f32_e32 v115, v115
	v_mfma_f32_16x16x32_bf16 v[26:29], v[206:209], v[82:85], v[26:29]
	v_exp_f32_e32 v116, v116
	v_mfma_f32_16x16x32_bf16 v[30:33], v[206:209], v[86:89], v[30:33]
	ds_read_b64_tr_b16 v[206:207], v245 offset:0
	ds_read_b64_tr_b16 v[208:209], v245 offset:4096
	v_exp_f32_e32 v117, v117
	s_waitcnt lgkmcnt(10)
	v_mfma_f32_16x16x32_bf16 v[34:37], v[210:213], v[82:85], v[34:37]
	v_exp_f32_e32 v118, v118
	v_mfma_f32_16x16x32_bf16 v[38:41], v[210:213], v[86:89], v[38:41]
	ds_read_b64_tr_b16 v[210:211], v238 offset:8192
	ds_read_b64_tr_b16 v[212:213], v238 offset:12288
	v_exp_f32_e32 v119, v119
	s_waitcnt lgkmcnt(10)
	v_mfma_f32_16x16x32_bf16 v[42:45], v[214:217], v[82:85], v[42:45]
	v_exp_f32_e32 v120, v120
	v_mfma_f32_16x16x32_bf16 v[46:49], v[214:217], v[86:89], v[46:49]
	ds_read_b64_tr_b16 v[214:215], v239 offset:8192
	ds_read_b64_tr_b16 v[216:217], v239 offset:12288
	v_exp_f32_e32 v121, v121
	s_waitcnt lgkmcnt(10)
	v_mfma_f32_16x16x32_bf16 v[50:53], v[218:221], v[82:85], v[50:53]
	v_exp_f32_e32 v122, v122
	v_mfma_f32_16x16x32_bf16 v[54:57], v[218:221], v[86:89], v[54:57]
	ds_read_b64_tr_b16 v[218:219], v240 offset:8192
	ds_read_b64_tr_b16 v[220:221], v240 offset:12288
	v_exp_f32_e32 v123, v123
	s_waitcnt lgkmcnt(10)
	v_mfma_f32_16x16x32_bf16 v[58:61], v[222:225], v[82:85], v[58:61]
	v_exp_f32_e32 v124, v124
	v_mfma_f32_16x16x32_bf16 v[62:65], v[222:225], v[86:89], v[62:65]
	ds_read_b64_tr_b16 v[222:223], v241 offset:8192
	ds_read_b64_tr_b16 v[224:225], v241 offset:12288
	v_exp_f32_e32 v125, v125
	s_waitcnt lgkmcnt(10)
	v_mfma_f32_16x16x32_bf16 v[66:69], v[202:205], v[82:85], v[66:69]
	v_exp_f32_e32 v126, v126
	v_mfma_f32_16x16x32_bf16 v[70:73], v[202:205], v[86:89], v[70:73]
	ds_read_b64_tr_b16 v[202:203], v242 offset:8192
	ds_read_b64_tr_b16 v[204:205], v242 offset:12288
	v_exp_f32_e32 v127, v127
	s_waitcnt lgkmcnt(10)
	v_mfma_f32_16x16x32_bf16 v[74:77], v[206:209], v[82:85], v[74:77]
	v_exp_f32_e32 v128, v128
	v_mfma_f32_16x16x32_bf16 v[78:81], v[206:209], v[86:89], v[78:81]
	ds_read_b64_tr_b16 v[206:207], v243 offset:8192
	ds_read_b64_tr_b16 v[208:209], v243 offset:12288
	v_exp_f32_e32 v129, v129
	s_waitcnt lgkmcnt(10)
	v_mfma_f32_16x16x32_bf16 v[18:21], v[210:213], v[98:101], v[18:21]
	v_exp_f32_e32 v130, v130
	v_mfma_f32_16x16x32_bf16 v[22:25], v[210:213], v[102:105], v[22:25]
	ds_read_b64_tr_b16 v[210:211], v244 offset:8192
	ds_read_b64_tr_b16 v[212:213], v244 offset:12288
	v_exp_f32_e32 v131, v131
	s_waitcnt lgkmcnt(10)
	v_mfma_f32_16x16x32_bf16 v[26:29], v[214:217], v[98:101], v[26:29]
	v_exp_f32_e32 v132, v132
	v_mfma_f32_16x16x32_bf16 v[30:33], v[214:217], v[102:105], v[30:33]
	ds_read_b64_tr_b16 v[214:215], v245 offset:8192
	ds_read_b64_tr_b16 v[216:217], v245 offset:12288
	v_exp_f32_e32 v133, v133
	s_waitcnt lgkmcnt(10)
	v_mfma_f32_16x16x32_bf16 v[34:37], v[218:221], v[98:101], v[34:37]
	v_exp_f32_e32 v134, v134
	v_mfma_f32_16x16x32_bf16 v[38:41], v[218:221], v[102:105], v[38:41]
	v_exp_f32_e32 v135, v135
	s_waitcnt lgkmcnt(8)
	v_mfma_f32_16x16x32_bf16 v[42:45], v[222:225], v[98:101], v[42:45]
	v_exp_f32_e32 v136, v136
	v_mfma_f32_16x16x32_bf16 v[46:49], v[222:225], v[102:105], v[46:49]
	v_exp_f32_e32 v137, v137
	s_waitcnt lgkmcnt(6)
	v_mfma_f32_16x16x32_bf16 v[50:53], v[202:205], v[98:101], v[50:53]
	v_exp_f32_e32 v138, v138
	ds_read_b128 v[178:181], v234 offset:32768
	v_mfma_f32_16x16x32_bf16 v[54:57], v[202:205], v[102:105], v[54:57]
	v_exp_f32_e32 v139, v139
	s_waitcnt lgkmcnt(5)
	v_mfma_f32_16x16x32_bf16 v[58:61], v[206:209], v[98:101], v[58:61]
	v_exp_f32_e32 v140, v140
	ds_read_b128 v[182:185], v234 offset:36864
	v_mfma_f32_16x16x32_bf16 v[62:65], v[206:209], v[102:105], v[62:65]
	v_exp_f32_e32 v141, v141
	s_waitcnt lgkmcnt(4)
	v_mfma_f32_16x16x32_bf16 v[66:69], v[210:213], v[98:101], v[66:69]
	v_exp_f32_e32 v142, v142
	ds_read_b128 v[186:189], v234 offset:40960
	v_mfma_f32_16x16x32_bf16 v[70:73], v[210:213], v[102:105], v[70:73]
	v_exp_f32_e32 v143, v143
	s_waitcnt lgkmcnt(3)
	v_mfma_f32_16x16x32_bf16 v[74:77], v[214:217], v[98:101], v[74:77]
	v_exp_f32_e32 v144, v144
	ds_read_b128 v[190:193], v234 offset:45056
	v_mfma_f32_16x16x32_bf16 v[78:81], v[214:217], v[102:105], v[78:81]
	v_exp_f32_e32 v145, v145
	s_waitcnt vmcnt(2)
	s_barrier
; __device__ __forceinline__ void partialSM(f32x16& p0, f32x16& p1, float mC) {
;   (void)mC; (void)p1;
;   for (int r = 0; r < 16; ++r) p0[r] = __builtin_amdgcn_exp2f(p0[r]);
; }
; __device__ __forceinline__ void finishSM(f32x16& p0, f32x16& p1, float& l_reg, bf16x8& pa0, bf16x8& pa1, bf16x8& pa2, bf16x8& pa3) {
;   for (int r = 0; r < 16; ++r) p1[r] = __builtin_amdgcn_exp2f(p1[r]);
;   float ps = 0; for (int r = 0; r < 16; ++r) ps += p0[r]; for (int r = 0; r < 16; ++r) ps += p1[r];
;   { auto rr = __builtin_amdgcn_permlane32_swap(__float_as_uint(ps), __float_as_uint(ps), false, false);
;     ps = __uint_as_float(rr[0]) + __uint_as_float(rr[1]); }
;   l_reg += ps;
;     ...
;   PK4(p0, 0, pa0); PK4(p0, 8, pa1); PK4(p1, 0, pa2); PK4(p1, 8, pa3);
;     ...
; }
; __device__ __forceinline__ void qkt(f32x16& p0, f32x16& p1, const bf16* Ks, const bf16x8* qr, int r32, int hi, const f32x16& negm) {
; #pragma unroll
;   for (int d0 = 0; d0 < 8; ++d0) { int cb = (d0 * 16 + hi * 8) * 2;
;     bf16x8 b0 = *reinterpret_cast<const bf16x8*>((const char*)Ks + KSWZ(r32, cb));
;     bf16x8 b1 = *reinterpret_cast<const bf16x8*>((const char*)Ks + KSWZ(32 + r32, cb));
;     if (d0 == 0) { p0 = __builtin_amdgcn_mfma_f32_32x32x16_bf16(b0, qr[0], negm, 0, 0, 0); p1 = __builtin_amdgcn_mfma_f32_32x32x16_bf16(b1, qr[0], negm, 0, 0, 0); }
;     else { p0 = __builtin_amdgcn_mfma_f32_32x32x16_bf16(b0, qr[d0], p0, 0, 0, 0); p1 = __builtin_amdgcn_mfma_f32_32x32x16_bf16(b1, qr[d0], p1, 0, 0, 0); } }
; }
; __device__ __forceinline__ int v_st(int k, int c) { const int kk = (k & ~0xC) | ((k & 4) << 1) | ((k & 8) >> 1); return ((kk >> 3) * 4 + (c >> 5)) * 512 + ((kk & 7) * 32 + (c & 31)) * 2; }
; __device__ __forceinline__ int v_rd_base(int lane) { return ((lane & 3) << 3) | (((lane >> 2) & 3) << 6) | (((lane >> 4) & 1) << 5) | (((lane >> 5) & 1) << 8); }
; template <int OFF> __device__ __forceinline__ s16x4 tr_read(int vb) {
;   s16x4 r; asm volatile("ds_read_b64_tr_b16 %0, %1 offset:%2" : "=&v"(r) : "v"(vb), "i"(OFF) : "memory"); return r;
; }
; template <int D0> __device__ __forceinline__ void pv_one(f32x16& od, int vb, bf16x8 pa0, bf16x8 pa1, bf16x8 pa2, bf16x8 pa3) {
;   const s16x4 l0 = tr_read<v_rd_off(D0, 0, 0)>(vb), h0 = tr_read<v_rd_off(D0, 0, 1)>(vb), l1 = tr_read<v_rd_off(D0, 1, 0)>(vb), h1 = tr_read<v_rd_off(D0, 1, 1)>(vb);
	s_waitcnt lgkmcnt(3)
	v_mfma_f32_16x16x32_bf16 v[82:85], v[178:181], v[146:149], v[2:5]
	v_add_f32_e32 v250, v114, v250
	v_mfma_f32_16x16x32_bf16 v[86:89], v[178:181], v[162:165], v[2:5]
	ds_read_b128 v[178:181], v235 offset:32768
	v_add_f32_e32 v250, v115, v250
	v_add_f32_e32 v250, v116, v250
	s_waitcnt lgkmcnt(3)
	v_mfma_f32_16x16x32_bf16 v[90:93], v[182:185], v[146:149], v[2:5]
	v_add_f32_e32 v250, v117, v250
	v_mfma_f32_16x16x32_bf16 v[94:97], v[182:185], v[162:165], v[2:5]
	ds_read_b128 v[182:185], v235 offset:36864
	v_add_f32_e32 v250, v122, v250
	v_add_f32_e32 v250, v123, v250
	s_waitcnt lgkmcnt(3)
	v_mfma_f32_16x16x32_bf16 v[98:101], v[186:189], v[146:149], v[2:5]
	v_add_f32_e32 v250, v124, v250
	v_mfma_f32_16x16x32_bf16 v[102:105], v[186:189], v[162:165], v[2:5]
	ds_read_b128 v[186:189], v235 offset:40960
	v_add_f32_e32 v250, v125, v250
	v_cvt_pk_bf16_f32 v114, v114, v115
	s_waitcnt lgkmcnt(3)
	v_mfma_f32_16x16x32_bf16 v[106:109], v[190:193], v[146:149], v[2:5]
	v_cvt_pk_bf16_f32 v115, v116, v117
	v_mfma_f32_16x16x32_bf16 v[110:113], v[190:193], v[162:165], v[2:5]
	ds_read_b128 v[190:193], v235 offset:45056
	v_cvt_pk_bf16_f32 v116, v122, v123
	v_cvt_pk_bf16_f32 v117, v124, v125
	s_waitcnt lgkmcnt(3)
	v_mfma_f32_16x16x32_bf16 v[82:85], v[178:181], v[150:153], v[82:85]
	v_add_f32_e32 v251, v118, v251
	v_mfma_f32_16x16x32_bf16 v[86:89], v[178:181], v[166:169], v[86:89]
	ds_read_b128 v[178:181], v236 offset:32768
	v_add_f32_e32 v251, v119, v251
	v_add_f32_e32 v251, v120, v251
	s_waitcnt lgkmcnt(3)
	v_mfma_f32_16x16x32_bf16 v[90:93], v[182:185], v[150:153], v[90:93]
	v_add_f32_e32 v251, v121, v251
	v_mfma_f32_16x16x32_bf16 v[94:97], v[182:185], v[166:169], v[94:97]
	ds_read_b128 v[182:185], v236 offset:36864
	v_add_f32_e32 v251, v126, v251
	v_add_f32_e32 v251, v127, v251
	s_waitcnt lgkmcnt(3)
	v_mfma_f32_16x16x32_bf16 v[98:101], v[186:189], v[150:153], v[98:101]
	v_add_f32_e32 v251, v128, v251
	v_mfma_f32_16x16x32_bf16 v[102:105], v[186:189], v[166:169], v[102:105]
	ds_read_b128 v[186:189], v236 offset:40960
	v_add_f32_e32 v251, v129, v251
	v_cvt_pk_bf16_f32 v118, v118, v119
	s_waitcnt lgkmcnt(3)
	v_mfma_f32_16x16x32_bf16 v[106:109], v[190:193], v[150:153], v[106:109]
	v_cvt_pk_bf16_f32 v119, v120, v121
	v_mfma_f32_16x16x32_bf16 v[110:113], v[190:193], v[166:169], v[110:113]
	ds_read_b128 v[190:193], v236 offset:45056
	v_cvt_pk_bf16_f32 v120, v126, v127
	v_cvt_pk_bf16_f32 v121, v128, v129
	s_waitcnt lgkmcnt(3)
	v_mfma_f32_16x16x32_bf16 v[82:85], v[178:181], v[154:157], v[82:85]
	v_add_f32_e32 v250, v130, v250
	v_mfma_f32_16x16x32_bf16 v[86:89], v[178:181], v[170:173], v[86:89]
	ds_read_b128 v[178:181], v237 offset:32768
	v_add_f32_e32 v250, v131, v250
	v_add_f32_e32 v250, v132, v250
	s_waitcnt lgkmcnt(3)
	v_mfma_f32_16x16x32_bf16 v[90:93], v[182:185], v[154:157], v[90:93]
	v_add_f32_e32 v250, v133, v250
	v_mfma_f32_16x16x32_bf16 v[94:97], v[182:185], v[170:173], v[94:97]
	ds_read_b128 v[182:185], v237 offset:36864
	v_add_f32_e32 v250, v138, v250
	v_add_f32_e32 v250, v139, v250
	s_waitcnt lgkmcnt(3)
	v_mfma_f32_16x16x32_bf16 v[98:101], v[186:189], v[154:157], v[98:101]
	v_add_f32_e32 v250, v140, v250
	ds_read_b64_tr_b16 v[202:203], v238 offset:16384
	ds_read_b64_tr_b16 v[204:205], v238 offset:20480
	v_mfma_f32_16x16x32_bf16 v[102:105], v[186:189], v[170:173], v[102:105]
	ds_read_b128 v[186:189], v237 offset:40960
	v_add_f32_e32 v250, v141, v250
	v_cvt_pk_bf16_f32 v130, v130, v131
	s_waitcnt lgkmcnt(5)
	v_mfma_f32_16x16x32_bf16 v[106:109], v[190:193], v[154:157], v[106:109]
	v_cvt_pk_bf16_f32 v131, v132, v133
	ds_read_b64_tr_b16 v[206:207], v239 offset:16384
	ds_read_b64_tr_b16 v[208:209], v239 offset:20480
	v_mfma_f32_16x16x32_bf16 v[110:113], v[190:193], v[170:173], v[110:113]
	ds_read_b128 v[190:193], v237 offset:45056
	v_cvt_pk_bf16_f32 v132, v138, v139
	v_cvt_pk_bf16_f32 v133, v140, v141
	s_waitcnt lgkmcnt(7)
	v_mfma_f32_16x16x32_bf16 v[82:85], v[178:181], v[158:161], v[82:85]
	v_add_f32_e32 v251, v134, v251
	ds_read_b64_tr_b16 v[210:211], v240 offset:16384
	ds_read_b64_tr_b16 v[212:213], v240 offset:20480
	v_mfma_f32_16x16x32_bf16 v[86:89], v[178:181], v[174:177], v[86:89]
	v_add_f32_e32 v251, v135, v251
	v_add_f32_e32 v251, v136, v251
	s_waitcnt lgkmcnt(8)
	v_mfma_f32_16x16x32_bf16 v[90:93], v[182:185], v[158:161], v[90:93]
	v_add_f32_e32 v251, v137, v251
	ds_read_b64_tr_b16 v[214:215], v241 offset:16384
	ds_read_b64_tr_b16 v[216:217], v241 offset:20480
	v_mfma_f32_16x16x32_bf16 v[94:97], v[182:185], v[174:177], v[94:97]
	v_add_f32_e32 v251, v142, v251
	v_add_f32_e32 v251, v143, v251
	s_waitcnt lgkmcnt(7)
	v_mfma_f32_16x16x32_bf16 v[98:101], v[186:189], v[158:161], v[98:101]
	v_add_f32_e32 v251, v144, v251
	ds_read_b64_tr_b16 v[218:219], v242 offset:16384
	ds_read_b64_tr_b16 v[220:221], v242 offset:20480
	v_mfma_f32_16x16x32_bf16 v[102:105], v[186:189], v[174:177], v[102:105]
	v_add_f32_e32 v251, v145, v251
	v_cvt_pk_bf16_f32 v134, v134, v135
	s_waitcnt lgkmcnt(6)
	v_mfma_f32_16x16x32_bf16 v[106:109], v[190:193], v[158:161], v[106:109]
	v_cvt_pk_bf16_f32 v135, v136, v137
	ds_read_b64_tr_b16 v[222:223], v243 offset:16384
	ds_read_b64_tr_b16 v[224:225], v243 offset:20480
	v_mfma_f32_16x16x32_bf16 v[110:113], v[190:193], v[174:177], v[110:113]
	v_cvt_pk_bf16_f32 v136, v142, v143
	v_cvt_pk_bf16_f32 v137, v144, v145
	v_mfma_f32_16x16x32_bf16 v[18:21], v[202:205], v[114:117], v[18:21]
	v_exp_f32_e32 v82, v82
	v_mfma_f32_16x16x32_bf16 v[22:25], v[202:205], v[118:121], v[22:25]
	ds_read_b64_tr_b16 v[202:203], v244 offset:16384
	ds_read_b64_tr_b16 v[204:205], v244 offset:20480
	v_exp_f32_e32 v83, v83
	v_mfma_f32_16x16x32_bf16 v[26:29], v[206:209], v[114:117], v[26:29]
	v_exp_f32_e32 v84, v84
	v_mfma_f32_16x16x32_bf16 v[30:33], v[206:209], v[118:121], v[30:33]
	ds_read_b64_tr_b16 v[206:207], v245 offset:16384
	ds_read_b64_tr_b16 v[208:209], v245 offset:20480
	v_exp_f32_e32 v85, v85
	s_waitcnt lgkmcnt(10)
; __device__ __forceinline__ void partialSM(f32x16& p0, f32x16& p1, float mC) {
;   (void)mC; (void)p1;
;   for (int r = 0; r < 16; ++r) p0[r] = __builtin_amdgcn_exp2f(p0[r]);
; }
; __device__ __forceinline__ void finishSM(f32x16& p0, f32x16& p1, float& l_reg, bf16x8& pa0, bf16x8& pa1, bf16x8& pa2, bf16x8& pa3) {
;   for (int r = 0; r < 16; ++r) p1[r] = __builtin_amdgcn_exp2f(p1[r]);
;   float ps = 0; for (int r = 0; r < 16; ++r) ps += p0[r]; for (int r = 0; r < 16; ++r) ps += p1[r];
;   { auto rr = __builtin_amdgcn_permlane32_swap(__float_as_uint(ps), __float_as_uint(ps), false, false);
;     ps = __uint_as_float(rr[0]) + __uint_as_float(rr[1]); }
;   l_reg += ps;
;     ...
;   PK4(p0, 0, pa0); PK4(p0, 8, pa1); PK4(p1, 0, pa2); PK4(p1, 8, pa3);
;     ...
; }
; __device__ __forceinline__ void qkt(f32x16& p0, f32x16& p1, const bf16* Ks, const bf16x8* qr, int r32, int hi, const f32x16& negm) {
; #pragma unroll
;   for (int d0 = 0; d0 < 8; ++d0) { int cb = (d0 * 16 + hi * 8) * 2;
;     bf16x8 b0 = *reinterpret_cast<const bf16x8*>((const char*)Ks + KSWZ(r32, cb));
;     bf16x8 b1 = *reinterpret_cast<const bf16x8*>((const char*)Ks + KSWZ(32 + r32, cb));
;     if (d0 == 0) { p0 = __builtin_amdgcn_mfma_f32_32x32x16_bf16(b0, qr[0], negm, 0, 0, 0); p1 = __builtin_amdgcn_mfma_f32_32x32x16_bf16(b1, qr[0], negm, 0, 0, 0); }
;     else { p0 = __builtin_amdgcn_mfma_f32_32x32x16_bf16(b0, qr[d0], p0, 0, 0, 0); p1 = __builtin_amdgcn_mfma_f32_32x32x16_bf16(b1, qr[d0], p1, 0, 0, 0); } }
; }
; __device__ __forceinline__ int v_st(int k, int c) { const int kk = (k & ~0xC) | ((k & 4) << 1) | ((k & 8) >> 1); return ((kk >> 3) * 4 + (c >> 5)) * 512 + ((kk & 7) * 32 + (c & 31)) * 2; }
; __device__ __forceinline__ int v_rd_base(int lane) { return ((lane & 3) << 3) | (((lane >> 2) & 3) << 6) | (((lane >> 4) & 1) << 5) | (((lane >> 5) & 1) << 8); }
; template <int OFF> __device__ __forceinline__ s16x4 tr_read(int vb) {
;   s16x4 r; asm volatile("ds_read_b64_tr_b16 %0, %1 offset:%2" : "=&v"(r) : "v"(vb), "i"(OFF) : "memory"); return r;
; }
; template <int D0> __device__ __forceinline__ void pv_one(f32x16& od, int vb, bf16x8 pa0, bf16x8 pa1, bf16x8 pa2, bf16x8 pa3) {
;   const s16x4 l0 = tr_read<v_rd_off(D0, 0, 0)>(vb), h0 = tr_read<v_rd_off(D0, 0, 1)>(vb), l1 = tr_read<v_rd_off(D0, 1, 0)>(vb), h1 = tr_read<v_rd_off(D0, 1, 1)>(vb);
	v_mfma_f32_16x16x32_bf16 v[34:37], v[210:213], v[114:117], v[34:37]
	v_exp_f32_e32 v86, v86
	v_mfma_f32_16x16x32_bf16 v[38:41], v[210:213], v[118:121], v[38:41]
	ds_read_b64_tr_b16 v[210:211], v238 offset:24576
	ds_read_b64_tr_b16 v[212:213], v238 offset:28672
	v_exp_f32_e32 v87, v87
	s_waitcnt lgkmcnt(10)
	v_mfma_f32_16x16x32_bf16 v[42:45], v[214:217], v[114:117], v[42:45]
	v_exp_f32_e32 v88, v88
	v_mfma_f32_16x16x32_bf16 v[46:49], v[214:217], v[118:121], v[46:49]
	ds_read_b64_tr_b16 v[214:215], v239 offset:24576
	ds_read_b64_tr_b16 v[216:217], v239 offset:28672
	v_exp_f32_e32 v89, v89
	s_waitcnt lgkmcnt(10)
	v_mfma_f32_16x16x32_bf16 v[50:53], v[218:221], v[114:117], v[50:53]
	v_exp_f32_e32 v90, v90
	v_mfma_f32_16x16x32_bf16 v[54:57], v[218:221], v[118:121], v[54:57]
	ds_read_b64_tr_b16 v[218:219], v240 offset:24576
	ds_read_b64_tr_b16 v[220:221], v240 offset:28672
	v_exp_f32_e32 v91, v91
	s_waitcnt lgkmcnt(10)
	v_mfma_f32_16x16x32_bf16 v[58:61], v[222:225], v[114:117], v[58:61]
	v_exp_f32_e32 v92, v92
	v_mfma_f32_16x16x32_bf16 v[62:65], v[222:225], v[118:121], v[62:65]
	ds_read_b64_tr_b16 v[222:223], v241 offset:24576
	ds_read_b64_tr_b16 v[224:225], v241 offset:28672
	v_exp_f32_e32 v93, v93
	s_waitcnt lgkmcnt(10)
	v_mfma_f32_16x16x32_bf16 v[66:69], v[202:205], v[114:117], v[66:69]
	v_exp_f32_e32 v94, v94
	v_mfma_f32_16x16x32_bf16 v[70:73], v[202:205], v[118:121], v[70:73]
	ds_read_b64_tr_b16 v[202:203], v242 offset:24576
	ds_read_b64_tr_b16 v[204:205], v242 offset:28672
	v_exp_f32_e32 v95, v95
	s_waitcnt lgkmcnt(10)
	v_mfma_f32_16x16x32_bf16 v[74:77], v[206:209], v[114:117], v[74:77]
	v_exp_f32_e32 v96, v96
	v_mfma_f32_16x16x32_bf16 v[78:81], v[206:209], v[118:121], v[78:81]
	ds_read_b64_tr_b16 v[206:207], v243 offset:24576
	ds_read_b64_tr_b16 v[208:209], v243 offset:28672
	v_exp_f32_e32 v97, v97
	s_waitcnt lgkmcnt(10)
	v_mfma_f32_16x16x32_bf16 v[18:21], v[210:213], v[130:133], v[18:21]
	v_exp_f32_e32 v98, v98
	v_mfma_f32_16x16x32_bf16 v[22:25], v[210:213], v[134:137], v[22:25]
	ds_read_b64_tr_b16 v[210:211], v244 offset:24576
	ds_read_b64_tr_b16 v[212:213], v244 offset:28672
	v_exp_f32_e32 v99, v99
	s_waitcnt lgkmcnt(10)
	v_mfma_f32_16x16x32_bf16 v[26:29], v[214:217], v[130:133], v[26:29]
	v_exp_f32_e32 v100, v100
	v_mfma_f32_16x16x32_bf16 v[30:33], v[214:217], v[134:137], v[30:33]
	ds_read_b64_tr_b16 v[214:215], v245 offset:24576
	ds_read_b64_tr_b16 v[216:217], v245 offset:28672
	v_exp_f32_e32 v101, v101
	s_waitcnt lgkmcnt(10)
	v_mfma_f32_16x16x32_bf16 v[34:37], v[218:221], v[130:133], v[34:37]
	v_exp_f32_e32 v102, v102
	v_mfma_f32_16x16x32_bf16 v[38:41], v[218:221], v[134:137], v[38:41]
	v_exp_f32_e32 v103, v103
	s_waitcnt lgkmcnt(8)
	v_mfma_f32_16x16x32_bf16 v[42:45], v[222:225], v[130:133], v[42:45]
	v_exp_f32_e32 v104, v104
	v_mfma_f32_16x16x32_bf16 v[46:49], v[222:225], v[134:137], v[46:49]
	v_exp_f32_e32 v105, v105
	s_waitcnt lgkmcnt(6)
	v_mfma_f32_16x16x32_bf16 v[50:53], v[202:205], v[130:133], v[50:53]
	v_exp_f32_e32 v106, v106
	ds_read_b128 v[178:181], v234 offset:49152
	v_mfma_f32_16x16x32_bf16 v[54:57], v[202:205], v[134:137], v[54:57]
	v_exp_f32_e32 v107, v107
	s_waitcnt lgkmcnt(5)
	v_mfma_f32_16x16x32_bf16 v[58:61], v[206:209], v[130:133], v[58:61]
	v_exp_f32_e32 v108, v108
	ds_read_b128 v[182:185], v234 offset:53248
	v_mfma_f32_16x16x32_bf16 v[62:65], v[206:209], v[134:137], v[62:65]
	v_exp_f32_e32 v109, v109
	s_waitcnt lgkmcnt(4)
	v_mfma_f32_16x16x32_bf16 v[66:69], v[210:213], v[130:133], v[66:69]
	v_exp_f32_e32 v110, v110
	ds_read_b128 v[186:189], v234 offset:57344
	v_mfma_f32_16x16x32_bf16 v[70:73], v[210:213], v[134:137], v[70:73]
	v_exp_f32_e32 v111, v111
	s_waitcnt lgkmcnt(3)
	v_mfma_f32_16x16x32_bf16 v[74:77], v[214:217], v[130:133], v[74:77]
	v_exp_f32_e32 v112, v112
	ds_read_b128 v[190:193], v234 offset:61440
	v_mfma_f32_16x16x32_bf16 v[78:81], v[214:217], v[134:137], v[78:81]
	v_exp_f32_e32 v113, v113
	s_waitcnt vmcnt(0)
	s_barrier
	s_waitcnt lgkmcnt(3)
	v_mfma_f32_16x16x32_bf16 v[114:117], v[178:181], v[146:149], v[2:5]
	v_add_f32_e32 v250, v82, v250
	v_mfma_f32_16x16x32_bf16 v[118:121], v[178:181], v[162:165], v[2:5]
	ds_read_b128 v[178:181], v235 offset:49152
	v_add_f32_e32 v250, v83, v250
	v_add_f32_e32 v250, v84, v250
	s_waitcnt lgkmcnt(3)
	v_mfma_f32_16x16x32_bf16 v[122:125], v[182:185], v[146:149], v[2:5]
	v_add_f32_e32 v250, v85, v250
	v_mfma_f32_16x16x32_bf16 v[126:129], v[182:185], v[162:165], v[2:5]
	ds_read_b128 v[182:185], v235 offset:53248
	v_add_f32_e32 v250, v90, v250
	v_add_f32_e32 v250, v91, v250
	s_waitcnt lgkmcnt(3)
	v_mfma_f32_16x16x32_bf16 v[130:133], v[186:189], v[146:149], v[2:5]
	v_add_f32_e32 v250, v92, v250
	v_mfma_f32_16x16x32_bf16 v[134:137], v[186:189], v[162:165], v[2:5]
	ds_read_b128 v[186:189], v235 offset:57344
	v_add_f32_e32 v250, v93, v250
	v_cvt_pk_bf16_f32 v82, v82, v83
	s_waitcnt lgkmcnt(3)
	v_mfma_f32_16x16x32_bf16 v[138:141], v[190:193], v[146:149], v[2:5]
	v_cvt_pk_bf16_f32 v83, v84, v85
	v_mfma_f32_16x16x32_bf16 v[142:145], v[190:193], v[162:165], v[2:5]
	ds_read_b128 v[190:193], v235 offset:61440
	v_cvt_pk_bf16_f32 v84, v90, v91
	v_cvt_pk_bf16_f32 v85, v92, v93
	s_waitcnt lgkmcnt(3)
	v_mfma_f32_16x16x32_bf16 v[114:117], v[178:181], v[150:153], v[114:117]
	v_add_f32_e32 v251, v86, v251
	v_mfma_f32_16x16x32_bf16 v[118:121], v[178:181], v[166:169], v[118:121]
	ds_read_b128 v[178:181], v236 offset:49152
	v_add_f32_e32 v251, v87, v251
	v_add_f32_e32 v251, v88, v251
	s_waitcnt lgkmcnt(3)
	v_mfma_f32_16x16x32_bf16 v[122:125], v[182:185], v[150:153], v[122:125]
	v_add_f32_e32 v251, v89, v251
	v_mfma_f32_16x16x32_bf16 v[126:129], v[182:185], v[166:169], v[126:129]
	ds_read_b128 v[182:185], v236 offset:53248
	v_add_f32_e32 v251, v94, v251
	v_add_f32_e32 v251, v95, v251
	s_waitcnt lgkmcnt(3)
; __device__ __forceinline__ void partialSM(f32x16& p0, f32x16& p1, float mC) {
;   (void)mC; (void)p1;
;   for (int r = 0; r < 16; ++r) p0[r] = __builtin_amdgcn_exp2f(p0[r]);
; }
; __device__ __forceinline__ void finishSM(f32x16& p0, f32x16& p1, float& l_reg, bf16x8& pa0, bf16x8& pa1, bf16x8& pa2, bf16x8& pa3) {
;   for (int r = 0; r < 16; ++r) p1[r] = __builtin_amdgcn_exp2f(p1[r]);
;   float ps = 0; for (int r = 0; r < 16; ++r) ps += p0[r]; for (int r = 0; r < 16; ++r) ps += p1[r];
;   { auto rr = __builtin_amdgcn_permlane32_swap(__float_as_uint(ps), __float_as_uint(ps), false, false);
;     ps = __uint_as_float(rr[0]) + __uint_as_float(rr[1]); }
;   l_reg += ps;
;     ...
;   PK4(p0, 0, pa0); PK4(p0, 8, pa1); PK4(p1, 0, pa2); PK4(p1, 8, pa3);
;     ...
; }
; __device__ __forceinline__ void qkt(f32x16& p0, f32x16& p1, const bf16* Ks, const bf16x8* qr, int r32, int hi, const f32x16& negm) {
; #pragma unroll
;   for (int d0 = 0; d0 < 8; ++d0) { int cb = (d0 * 16 + hi * 8) * 2;
;     bf16x8 b0 = *reinterpret_cast<const bf16x8*>((const char*)Ks + KSWZ(r32, cb));
;     bf16x8 b1 = *reinterpret_cast<const bf16x8*>((const char*)Ks + KSWZ(32 + r32, cb));
;     if (d0 == 0) { p0 = __builtin_amdgcn_mfma_f32_32x32x16_bf16(b0, qr[0], negm, 0, 0, 0); p1 = __builtin_amdgcn_mfma_f32_32x32x16_bf16(b1, qr[0], negm, 0, 0, 0); }
;     else { p0 = __builtin_amdgcn_mfma_f32_32x32x16_bf16(b0, qr[d0], p0, 0, 0, 0); p1 = __builtin_amdgcn_mfma_f32_32x32x16_bf16(b1, qr[d0], p1, 0, 0, 0); } }
; }
; __device__ __forceinline__ int v_st(int k, int c) { const int kk = (k & ~0xC) | ((k & 4) << 1) | ((k & 8) >> 1); return ((kk >> 3) * 4 + (c >> 5)) * 512 + ((kk & 7) * 32 + (c & 31)) * 2; }
; __device__ __forceinline__ int v_rd_base(int lane) { return ((lane & 3) << 3) | (((lane >> 2) & 3) << 6) | (((lane >> 4) & 1) << 5) | (((lane >> 5) & 1) << 8); }
; template <int OFF> __device__ __forceinline__ s16x4 tr_read(int vb) {
;   s16x4 r; asm volatile("ds_read_b64_tr_b16 %0, %1 offset:%2" : "=&v"(r) : "v"(vb), "i"(OFF) : "memory"); return r;
; }
; template <int D0> __device__ __forceinline__ void pv_one(f32x16& od, int vb, bf16x8 pa0, bf16x8 pa1, bf16x8 pa2, bf16x8 pa3) {
;   const s16x4 l0 = tr_read<v_rd_off(D0, 0, 0)>(vb), h0 = tr_read<v_rd_off(D0, 0, 1)>(vb), l1 = tr_read<v_rd_off(D0, 1, 0)>(vb), h1 = tr_read<v_rd_off(D0, 1, 1)>(vb);
	v_mfma_f32_16x16x32_bf16 v[130:133], v[186:189], v[150:153], v[130:133]
	v_add_f32_e32 v251, v96, v251
	v_mfma_f32_16x16x32_bf16 v[134:137], v[186:189], v[166:169], v[134:137]
	ds_read_b128 v[186:189], v236 offset:57344
	v_add_f32_e32 v251, v97, v251
	v_cvt_pk_bf16_f32 v86, v86, v87
	s_waitcnt lgkmcnt(3)
	v_mfma_f32_16x16x32_bf16 v[138:141], v[190:193], v[150:153], v[138:141]
	v_cvt_pk_bf16_f32 v87, v88, v89
	v_mfma_f32_16x16x32_bf16 v[142:145], v[190:193], v[166:169], v[142:145]
	ds_read_b128 v[190:193], v236 offset:61440
	v_cvt_pk_bf16_f32 v88, v94, v95
	v_cvt_pk_bf16_f32 v89, v96, v97
	s_waitcnt lgkmcnt(3)
	v_mfma_f32_16x16x32_bf16 v[114:117], v[178:181], v[154:157], v[114:117]
	v_add_f32_e32 v250, v98, v250
	v_mfma_f32_16x16x32_bf16 v[118:121], v[178:181], v[170:173], v[118:121]
	ds_read_b128 v[178:181], v237 offset:49152
	v_add_f32_e32 v250, v99, v250
	v_add_f32_e32 v250, v100, v250
	s_waitcnt lgkmcnt(3)
	v_mfma_f32_16x16x32_bf16 v[122:125], v[182:185], v[154:157], v[122:125]
	v_add_f32_e32 v250, v101, v250
	v_mfma_f32_16x16x32_bf16 v[126:129], v[182:185], v[170:173], v[126:129]
	ds_read_b128 v[182:185], v237 offset:53248
	v_add_f32_e32 v250, v106, v250
	v_add_f32_e32 v250, v107, v250
	s_waitcnt lgkmcnt(3)
	v_mfma_f32_16x16x32_bf16 v[130:133], v[186:189], v[154:157], v[130:133]
	v_add_f32_e32 v250, v108, v250
	ds_read_b64_tr_b16 v[202:203], v238 offset:32768
	ds_read_b64_tr_b16 v[204:205], v238 offset:36864
	v_mfma_f32_16x16x32_bf16 v[134:137], v[186:189], v[170:173], v[134:137]
	ds_read_b128 v[186:189], v237 offset:57344
	v_add_f32_e32 v250, v109, v250
	v_cvt_pk_bf16_f32 v98, v98, v99
	s_waitcnt lgkmcnt(5)
	v_mfma_f32_16x16x32_bf16 v[138:141], v[190:193], v[154:157], v[138:141]
	v_cvt_pk_bf16_f32 v99, v100, v101
	ds_read_b64_tr_b16 v[206:207], v239 offset:32768
	ds_read_b64_tr_b16 v[208:209], v239 offset:36864
	v_mfma_f32_16x16x32_bf16 v[142:145], v[190:193], v[170:173], v[142:145]
	ds_read_b128 v[190:193], v237 offset:61440
	v_cvt_pk_bf16_f32 v100, v106, v107
	v_cvt_pk_bf16_f32 v101, v108, v109
	s_waitcnt lgkmcnt(7)
	v_mfma_f32_16x16x32_bf16 v[114:117], v[178:181], v[158:161], v[114:117]
	v_add_f32_e32 v251, v102, v251
	ds_read_b64_tr_b16 v[210:211], v240 offset:32768
	ds_read_b64_tr_b16 v[212:213], v240 offset:36864
	v_mfma_f32_16x16x32_bf16 v[118:121], v[178:181], v[174:177], v[118:121]
	v_add_f32_e32 v251, v103, v251
	v_add_f32_e32 v251, v104, v251
	s_waitcnt lgkmcnt(8)
	v_mfma_f32_16x16x32_bf16 v[122:125], v[182:185], v[158:161], v[122:125]
	v_add_f32_e32 v251, v105, v251
	ds_read_b64_tr_b16 v[214:215], v241 offset:32768
	ds_read_b64_tr_b16 v[216:217], v241 offset:36864
	v_mfma_f32_16x16x32_bf16 v[126:129], v[182:185], v[174:177], v[126:129]
	v_add_f32_e32 v251, v110, v251
	v_add_f32_e32 v251, v111, v251
	s_waitcnt lgkmcnt(7)
	v_mfma_f32_16x16x32_bf16 v[130:133], v[186:189], v[158:161], v[130:133]
	v_add_f32_e32 v251, v112, v251
	ds_read_b64_tr_b16 v[218:219], v242 offset:32768
	ds_read_b64_tr_b16 v[220:221], v242 offset:36864
	v_mfma_f32_16x16x32_bf16 v[134:137], v[186:189], v[174:177], v[134:137]
	v_add_f32_e32 v251, v113, v251
	v_cvt_pk_bf16_f32 v102, v102, v103
	s_waitcnt lgkmcnt(6)
	v_mfma_f32_16x16x32_bf16 v[138:141], v[190:193], v[158:161], v[138:141]
	v_cvt_pk_bf16_f32 v103, v104, v105
	ds_read_b64_tr_b16 v[222:223], v243 offset:32768
	ds_read_b64_tr_b16 v[224:225], v243 offset:36864
	v_mfma_f32_16x16x32_bf16 v[142:145], v[190:193], v[174:177], v[142:145]
	v_cvt_pk_bf16_f32 v104, v110, v111
	v_cvt_pk_bf16_f32 v105, v112, v113
	v_mfma_f32_16x16x32_bf16 v[18:21], v[202:205], v[82:85], v[18:21]
	v_exp_f32_e32 v114, v114
	v_mfma_f32_16x16x32_bf16 v[22:25], v[202:205], v[86:89], v[22:25]
	ds_read_b64_tr_b16 v[202:203], v244 offset:32768
	ds_read_b64_tr_b16 v[204:205], v244 offset:36864
	v_exp_f32_e32 v115, v115
	v_mfma_f32_16x16x32_bf16 v[26:29], v[206:209], v[82:85], v[26:29]
	v_exp_f32_e32 v116, v116
	v_mfma_f32_16x16x32_bf16 v[30:33], v[206:209], v[86:89], v[30:33]
	ds_read_b64_tr_b16 v[206:207], v245 offset:32768
	ds_read_b64_tr_b16 v[208:209], v245 offset:36864
	v_exp_f32_e32 v117, v117
	s_waitcnt lgkmcnt(10)
	v_mfma_f32_16x16x32_bf16 v[34:37], v[210:213], v[82:85], v[34:37]
	v_exp_f32_e32 v118, v118
	v_mfma_f32_16x16x32_bf16 v[38:41], v[210:213], v[86:89], v[38:41]
	ds_read_b64_tr_b16 v[210:211], v238 offset:40960
	ds_read_b64_tr_b16 v[212:213], v238 offset:45056
	v_exp_f32_e32 v119, v119
	s_waitcnt lgkmcnt(10)
	v_mfma_f32_16x16x32_bf16 v[42:45], v[214:217], v[82:85], v[42:45]
	v_exp_f32_e32 v120, v120
	v_mfma_f32_16x16x32_bf16 v[46:49], v[214:217], v[86:89], v[46:49]
	ds_read_b64_tr_b16 v[214:215], v239 offset:40960
	ds_read_b64_tr_b16 v[216:217], v239 offset:45056
	v_exp_f32_e32 v121, v121
	s_waitcnt lgkmcnt(10)
	v_mfma_f32_16x16x32_bf16 v[50:53], v[218:221], v[82:85], v[50:53]
	v_exp_f32_e32 v122, v122
	v_mfma_f32_16x16x32_bf16 v[54:57], v[218:221], v[86:89], v[54:57]
	ds_read_b64_tr_b16 v[218:219], v240 offset:40960
	ds_read_b64_tr_b16 v[220:221], v240 offset:45056
	v_exp_f32_e32 v123, v123
	s_waitcnt lgkmcnt(10)
	v_mfma_f32_16x16x32_bf16 v[58:61], v[222:225], v[82:85], v[58:61]
	v_exp_f32_e32 v124, v124
	v_mfma_f32_16x16x32_bf16 v[62:65], v[222:225], v[86:89], v[62:65]
	ds_read_b64_tr_b16 v[222:223], v241 offset:40960
	ds_read_b64_tr_b16 v[224:225], v241 offset:45056
	v_exp_f32_e32 v125, v125
	s_waitcnt lgkmcnt(10)
	v_mfma_f32_16x16x32_bf16 v[66:69], v[202:205], v[82:85], v[66:69]
	v_exp_f32_e32 v126, v126
	v_mfma_f32_16x16x32_bf16 v[70:73], v[202:205], v[86:89], v[70:73]
	ds_read_b64_tr_b16 v[202:203], v242 offset:40960
	ds_read_b64_tr_b16 v[204:205], v242 offset:45056
	v_exp_f32_e32 v127, v127
	s_waitcnt lgkmcnt(10)
; __device__ __forceinline__ void partialSM(f32x16& p0, f32x16& p1, float mC) {
;   (void)mC; (void)p1;
;   for (int r = 0; r < 16; ++r) p0[r] = __builtin_amdgcn_exp2f(p0[r]);
; }
; __device__ __forceinline__ void finishSM(f32x16& p0, f32x16& p1, float& l_reg, bf16x8& pa0, bf16x8& pa1, bf16x8& pa2, bf16x8& pa3) {
;   for (int r = 0; r < 16; ++r) p1[r] = __builtin_amdgcn_exp2f(p1[r]);
;   float ps = 0; for (int r = 0; r < 16; ++r) ps += p0[r]; for (int r = 0; r < 16; ++r) ps += p1[r];
;   { auto rr = __builtin_amdgcn_permlane32_swap(__float_as_uint(ps), __float_as_uint(ps), false, false);
;     ps = __uint_as_float(rr[0]) + __uint_as_float(rr[1]); }
;   l_reg += ps;
;     ...
;   PK4(p0, 0, pa0); PK4(p0, 8, pa1); PK4(p1, 0, pa2); PK4(p1, 8, pa3);
;     ...
; }
; __device__ __forceinline__ void qkt(f32x16& p0, f32x16& p1, const bf16* Ks, const bf16x8* qr, int r32, int hi, const f32x16& negm) {
; #pragma unroll
;   for (int d0 = 0; d0 < 8; ++d0) { int cb = (d0 * 16 + hi * 8) * 2;
;     bf16x8 b0 = *reinterpret_cast<const bf16x8*>((const char*)Ks + KSWZ(r32, cb));
;     bf16x8 b1 = *reinterpret_cast<const bf16x8*>((const char*)Ks + KSWZ(32 + r32, cb));
;     if (d0 == 0) { p0 = __builtin_amdgcn_mfma_f32_32x32x16_bf16(b0, qr[0], negm, 0, 0, 0); p1 = __builtin_amdgcn_mfma_f32_32x32x16_bf16(b1, qr[0], negm, 0, 0, 0); }
;     else { p0 = __builtin_amdgcn_mfma_f32_32x32x16_bf16(b0, qr[d0], p0, 0, 0, 0); p1 = __builtin_amdgcn_mfma_f32_32x32x16_bf16(b1, qr[d0], p1, 0, 0, 0); } }
; }
; __device__ __forceinline__ int v_st(int k, int c) { const int kk = (k & ~0xC) | ((k & 4) << 1) | ((k & 8) >> 1); return ((kk >> 3) * 4 + (c >> 5)) * 512 + ((kk & 7) * 32 + (c & 31)) * 2; }
; __device__ __forceinline__ int v_rd_base(int lane) { return ((lane & 3) << 3) | (((lane >> 2) & 3) << 6) | (((lane >> 4) & 1) << 5) | (((lane >> 5) & 1) << 8); }
; template <int OFF> __device__ __forceinline__ s16x4 tr_read(int vb) {
;   s16x4 r; asm volatile("ds_read_b64_tr_b16 %0, %1 offset:%2" : "=&v"(r) : "v"(vb), "i"(OFF) : "memory"); return r;
; }
; template <int D0> __device__ __forceinline__ void pv_one(f32x16& od, int vb, bf16x8 pa0, bf16x8 pa1, bf16x8 pa2, bf16x8 pa3) {
;   const s16x4 l0 = tr_read<v_rd_off(D0, 0, 0)>(vb), h0 = tr_read<v_rd_off(D0, 0, 1)>(vb), l1 = tr_read<v_rd_off(D0, 1, 0)>(vb), h1 = tr_read<v_rd_off(D0, 1, 1)>(vb);
	v_mfma_f32_16x16x32_bf16 v[74:77], v[206:209], v[82:85], v[74:77]
	v_exp_f32_e32 v128, v128
	v_mfma_f32_16x16x32_bf16 v[78:81], v[206:209], v[86:89], v[78:81]
	ds_read_b64_tr_b16 v[206:207], v243 offset:40960
	ds_read_b64_tr_b16 v[208:209], v243 offset:45056
	v_exp_f32_e32 v129, v129
	s_waitcnt lgkmcnt(10)
	v_mfma_f32_16x16x32_bf16 v[18:21], v[210:213], v[98:101], v[18:21]
	v_exp_f32_e32 v130, v130
	v_mfma_f32_16x16x32_bf16 v[22:25], v[210:213], v[102:105], v[22:25]
	ds_read_b64_tr_b16 v[210:211], v244 offset:40960
	ds_read_b64_tr_b16 v[212:213], v244 offset:45056
	v_exp_f32_e32 v131, v131
	s_waitcnt lgkmcnt(10)
	v_mfma_f32_16x16x32_bf16 v[26:29], v[214:217], v[98:101], v[26:29]
	v_exp_f32_e32 v132, v132
	v_mfma_f32_16x16x32_bf16 v[30:33], v[214:217], v[102:105], v[30:33]
	ds_read_b64_tr_b16 v[214:215], v245 offset:40960
	ds_read_b64_tr_b16 v[216:217], v245 offset:45056
	v_exp_f32_e32 v133, v133
	s_waitcnt lgkmcnt(10)
	v_mfma_f32_16x16x32_bf16 v[34:37], v[218:221], v[98:101], v[34:37]
	v_exp_f32_e32 v134, v134
	v_mfma_f32_16x16x32_bf16 v[38:41], v[218:221], v[102:105], v[38:41]
	v_exp_f32_e32 v135, v135
	s_waitcnt lgkmcnt(8)
	v_mfma_f32_16x16x32_bf16 v[42:45], v[222:225], v[98:101], v[42:45]
	v_exp_f32_e32 v136, v136
	v_mfma_f32_16x16x32_bf16 v[46:49], v[222:225], v[102:105], v[46:49]
	v_exp_f32_e32 v137, v137
	s_waitcnt lgkmcnt(6)
	v_mfma_f32_16x16x32_bf16 v[50:53], v[202:205], v[98:101], v[50:53]
	v_exp_f32_e32 v138, v138
	v_mfma_f32_16x16x32_bf16 v[54:57], v[202:205], v[102:105], v[54:57]
	v_exp_f32_e32 v139, v139
	s_waitcnt lgkmcnt(4)
	v_mfma_f32_16x16x32_bf16 v[58:61], v[206:209], v[98:101], v[58:61]
	v_exp_f32_e32 v140, v140
	v_mfma_f32_16x16x32_bf16 v[62:65], v[206:209], v[102:105], v[62:65]
	v_exp_f32_e32 v141, v141
	s_waitcnt lgkmcnt(2)
	v_mfma_f32_16x16x32_bf16 v[66:69], v[210:213], v[98:101], v[66:69]
	v_exp_f32_e32 v142, v142
	v_mfma_f32_16x16x32_bf16 v[70:73], v[210:213], v[102:105], v[70:73]
	v_exp_f32_e32 v143, v143
	s_waitcnt lgkmcnt(0)
	v_mfma_f32_16x16x32_bf16 v[74:77], v[214:217], v[98:101], v[74:77]
	v_exp_f32_e32 v144, v144
	v_mfma_f32_16x16x32_bf16 v[78:81], v[214:217], v[102:105], v[78:81]
	v_exp_f32_e32 v145, v145
	s_waitcnt vmcnt(0)
	v_add_f32_e32 v250, v114, v250
	v_add_f32_e32 v250, v115, v250
	v_add_f32_e32 v250, v116, v250
	v_add_f32_e32 v250, v117, v250
	v_add_f32_e32 v250, v122, v250
	v_add_f32_e32 v250, v123, v250
	v_add_f32_e32 v250, v124, v250
	v_add_f32_e32 v250, v125, v250
	v_cvt_pk_bf16_f32 v114, v114, v115
	v_cvt_pk_bf16_f32 v115, v116, v117
	v_cvt_pk_bf16_f32 v116, v122, v123
	v_cvt_pk_bf16_f32 v117, v124, v125
	v_add_f32_e32 v251, v118, v251
	v_add_f32_e32 v251, v119, v251
	v_add_f32_e32 v251, v120, v251
	v_add_f32_e32 v251, v121, v251
	v_add_f32_e32 v251, v126, v251
	v_add_f32_e32 v251, v127, v251
	v_add_f32_e32 v251, v128, v251
	v_add_f32_e32 v251, v129, v251
	v_cvt_pk_bf16_f32 v118, v118, v119
	v_cvt_pk_bf16_f32 v119, v120, v121
	v_cvt_pk_bf16_f32 v120, v126, v127
	v_cvt_pk_bf16_f32 v121, v128, v129
	v_add_f32_e32 v250, v130, v250
	v_add_f32_e32 v250, v131, v250
	v_add_f32_e32 v250, v132, v250
	v_add_f32_e32 v250, v133, v250
	v_add_f32_e32 v250, v138, v250
	v_add_f32_e32 v250, v139, v250
	v_add_f32_e32 v250, v140, v250
	v_add_f32_e32 v250, v141, v250
	v_cvt_pk_bf16_f32 v130, v130, v131
	v_cvt_pk_bf16_f32 v131, v132, v133
	v_cvt_pk_bf16_f32 v132, v138, v139
	v_cvt_pk_bf16_f32 v133, v140, v141
	v_add_f32_e32 v251, v134, v251
	v_add_f32_e32 v251, v135, v251
	v_add_f32_e32 v251, v136, v251
	v_add_f32_e32 v251, v137, v251
	v_add_f32_e32 v251, v142, v251
	v_add_f32_e32 v251, v143, v251
	v_add_f32_e32 v251, v144, v251
	v_add_f32_e32 v251, v145, v251
	v_cvt_pk_bf16_f32 v134, v134, v135
	v_cvt_pk_bf16_f32 v135, v136, v137
	v_cvt_pk_bf16_f32 v136, v142, v143
	v_cvt_pk_bf16_f32 v137, v144, v145
	ds_read_b64_tr_b16 v[202:203], v238 offset:49152
	ds_read_b64_tr_b16 v[204:205], v238 offset:53248
	ds_read_b64_tr_b16 v[206:207], v239 offset:49152
	ds_read_b64_tr_b16 v[208:209], v239 offset:53248
	ds_read_b64_tr_b16 v[210:211], v240 offset:49152
	ds_read_b64_tr_b16 v[212:213], v240 offset:53248
	ds_read_b64_tr_b16 v[214:215], v241 offset:49152
	ds_read_b64_tr_b16 v[216:217], v241 offset:53248
	ds_read_b64_tr_b16 v[218:219], v242 offset:49152
	ds_read_b64_tr_b16 v[220:221], v242 offset:53248
	ds_read_b64_tr_b16 v[222:223], v243 offset:49152
	ds_read_b64_tr_b16 v[224:225], v243 offset:53248
	s_waitcnt lgkmcnt(10)
	v_mfma_f32_16x16x32_bf16 v[18:21], v[202:205], v[114:117], v[18:21]
	v_mfma_f32_16x16x32_bf16 v[22:25], v[202:205], v[118:121], v[22:25]
	ds_read_b64_tr_b16 v[202:203], v244 offset:49152
	ds_read_b64_tr_b16 v[204:205], v244 offset:53248
	s_waitcnt lgkmcnt(10)
	v_mfma_f32_16x16x32_bf16 v[26:29], v[206:209], v[114:117], v[26:29]
	v_mfma_f32_16x16x32_bf16 v[30:33], v[206:209], v[118:121], v[30:33]
	ds_read_b64_tr_b16 v[206:207], v245 offset:49152
	ds_read_b64_tr_b16 v[208:209], v245 offset:53248
	s_waitcnt lgkmcnt(10)
	v_mfma_f32_16x16x32_bf16 v[34:37], v[210:213], v[114:117], v[34:37]
	v_mfma_f32_16x16x32_bf16 v[38:41], v[210:213], v[118:121], v[38:41]
	ds_read_b64_tr_b16 v[210:211], v238 offset:57344
	ds_read_b64_tr_b16 v[212:213], v238 offset:61440
	s_waitcnt lgkmcnt(10)
	v_mfma_f32_16x16x32_bf16 v[42:45], v[214:217], v[114:117], v[42:45]
	v_mfma_f32_16x16x32_bf16 v[46:49], v[214:217], v[118:121], v[46:49]
	ds_read_b64_tr_b16 v[214:215], v239 offset:57344
	ds_read_b64_tr_b16 v[216:217], v239 offset:61440
	s_waitcnt lgkmcnt(10)
	v_mfma_f32_16x16x32_bf16 v[50:53], v[218:221], v[114:117], v[50:53]
	v_mfma_f32_16x16x32_bf16 v[54:57], v[218:221], v[118:121], v[54:57]
	ds_read_b64_tr_b16 v[218:219], v240 offset:57344
	ds_read_b64_tr_b16 v[220:221], v240 offset:61440
	s_waitcnt lgkmcnt(10)
; #define SBAR() __builtin_amdgcn_sched_barrier(0)
; __device__ __forceinline__ int crow(int r, int hi) { return (r & 3) + 8 * (r >> 2) + 4 * hi; }
; template <typename TQ> ...
;     ...
;   SBAR(); qkt(pB0, pB1, (bf16*)((char*)K_lds + SHM_K), qr, r32, hi, negm);
;   finishSM(pA0, pA1, l_reg, pa0, pa1, pa2, pa3); SBAR();
;   pv_d0(o, vb0, pa0, pa1, pa2, pa3); partialSM(pB0, pB1, mC);
;   __syncthreads();
;   finishSM(pB0, pB1, l_reg, pa0, pa1, pa2, pa3); SBAR();
;   pv_d0(o, vb0 + (int)SHM_V, pa0, pa1, pa2, pa3);
;   if (hi == 0) li_l[r32] = l_reg; asm volatile("s_waitcnt lgkmcnt(0)" ::: "memory");
;   float rli[16];
; #pragma unroll
;   for (int r = 0; r < 16; ++r) rli[r] = __builtin_amdgcn_rcpf(li_l[crow(r, hi)]);
;   int le = (int)(threadIdx.x & 63u); asm volatile("" : "+v"(le));
;   const int r32e = le & 31, hie = le >> 5;
;   bf16* Ow = Ob + (long)(wid * QBLK) * LDO;
; #pragma unroll
;   for (int r = 0; r < 16; ++r) { int orow = crow(r, hie);
;     for (int d0 = 0; d0 < 4; ++d0) Ow[(long)orow * LDO + d0 * 32 + r32e] = __float2bfloat16(o[d0][r] * rli[r]); }
; __global__ void __launch_bounds__(NTHR, 2) fwd_megakernel(KArgs a) {
;     ...
;         for (int i = 0; i < upb; ++i) {
;             const int unit = vcu * upb + i; if (unit >= 512) break;
;             const int grp = unit >> 7, rem = unit & 127, gq = rem >> 5, qb = rem & 31, b = grp >> 1, kvh = grp & 1, h = kvh * 4 + gq;
;             const size_t qoff = ((size_t)(b * SEQ + qb * 256)) * DM + h * 128, koff = (size_t)b * SKV * 256 + kvh * 128;
;             att::attn_dense_body<att::bf16>(Q + qoff, Kb + koff, Vb + koff, O + qoff, SKV, (char*)lds_raw, mC, a.g_q, (const float*)(ws + WS_ROPE), (const float*)(ws + WS_ROPE) + 4096, qb * 256);
;             __syncthreads();
;         }
	v_mfma_f32_16x16x32_bf16 v[58:61], v[222:225], v[114:117], v[58:61]
	v_mfma_f32_16x16x32_bf16 v[62:65], v[222:225], v[118:121], v[62:65]
	ds_read_b64_tr_b16 v[222:223], v241 offset:57344
	ds_read_b64_tr_b16 v[224:225], v241 offset:61440
	s_waitcnt lgkmcnt(10)
	v_mfma_f32_16x16x32_bf16 v[66:69], v[202:205], v[114:117], v[66:69]
	v_mfma_f32_16x16x32_bf16 v[70:73], v[202:205], v[118:121], v[70:73]
	ds_read_b64_tr_b16 v[202:203], v242 offset:57344
	ds_read_b64_tr_b16 v[204:205], v242 offset:61440
	s_waitcnt lgkmcnt(10)
	v_mfma_f32_16x16x32_bf16 v[74:77], v[206:209], v[114:117], v[74:77]
	v_mfma_f32_16x16x32_bf16 v[78:81], v[206:209], v[118:121], v[78:81]
	ds_read_b64_tr_b16 v[206:207], v243 offset:57344
	ds_read_b64_tr_b16 v[208:209], v243 offset:61440
	s_waitcnt lgkmcnt(10)
	v_mfma_f32_16x16x32_bf16 v[18:21], v[210:213], v[130:133], v[18:21]
	v_mfma_f32_16x16x32_bf16 v[22:25], v[210:213], v[134:137], v[22:25]
	ds_read_b64_tr_b16 v[210:211], v244 offset:57344
	ds_read_b64_tr_b16 v[212:213], v244 offset:61440
	s_waitcnt lgkmcnt(10)
	v_mfma_f32_16x16x32_bf16 v[26:29], v[214:217], v[130:133], v[26:29]
	v_mfma_f32_16x16x32_bf16 v[30:33], v[214:217], v[134:137], v[30:33]
	ds_read_b64_tr_b16 v[214:215], v245 offset:57344
	ds_read_b64_tr_b16 v[216:217], v245 offset:61440
	s_waitcnt lgkmcnt(10)
	v_mfma_f32_16x16x32_bf16 v[34:37], v[218:221], v[130:133], v[34:37]
	v_mfma_f32_16x16x32_bf16 v[38:41], v[218:221], v[134:137], v[38:41]
	s_waitcnt lgkmcnt(8)
	v_mfma_f32_16x16x32_bf16 v[42:45], v[222:225], v[130:133], v[42:45]
	v_mfma_f32_16x16x32_bf16 v[46:49], v[222:225], v[134:137], v[46:49]
	s_waitcnt lgkmcnt(6)
	v_mfma_f32_16x16x32_bf16 v[50:53], v[202:205], v[130:133], v[50:53]
	v_mfma_f32_16x16x32_bf16 v[54:57], v[202:205], v[134:137], v[54:57]
	s_waitcnt lgkmcnt(4)
	v_mfma_f32_16x16x32_bf16 v[58:61], v[206:209], v[130:133], v[58:61]
	v_mfma_f32_16x16x32_bf16 v[62:65], v[206:209], v[134:137], v[62:65]
	s_waitcnt lgkmcnt(2)
	v_mfma_f32_16x16x32_bf16 v[66:69], v[210:213], v[130:133], v[66:69]
	v_mfma_f32_16x16x32_bf16 v[70:73], v[210:213], v[134:137], v[70:73]
	s_waitcnt lgkmcnt(0)
	v_mfma_f32_16x16x32_bf16 v[74:77], v[214:217], v[130:133], v[74:77]
	v_mfma_f32_16x16x32_bf16 v[78:81], v[214:217], v[134:137], v[78:81]
	s_setprio 0
	ds_swizzle_b32 v6, v250 offset:swizzle(SWAP,16)
	s_waitcnt lgkmcnt(0)
	v_add_f32_e32 v250, v250, v6
	v_mov_b32_e32 v6, v250
	s_nop 1
	v_permlane32_swap_b32_e32 v250, v6
	v_add_f32_e32 v250, v250, v6
	v_rcp_f32_e32 v250, v250
	ds_swizzle_b32 v6, v251 offset:swizzle(SWAP,16)
	s_waitcnt lgkmcnt(0)
	v_add_f32_e32 v251, v251, v6
	v_mov_b32_e32 v6, v251
	s_nop 1
	v_permlane32_swap_b32_e32 v251, v6
	v_add_f32_e32 v251, v251, v6
	v_rcp_f32_e32 v251, v251
	s_add_u32 s12, s71, s48
	s_addc_u32 s13, s72, s49
	v_add_u32_e32 v201, s52, v16
	v_lshlrev_b32_e32 v201, 11, v201
	v_lshl_or_b32 v7, v17, 3, v201
	v_add_u32_e32 v200, 0x8000, v7
	v_mul_f32_e32 v18, v18, v250
	v_mul_f32_e32 v19, v19, v250
	v_mul_f32_e32 v20, v20, v250
	v_mul_f32_e32 v21, v21, v250
	v_cvt_pk_bf16_f32 v18, v18, v19
	v_cvt_pk_bf16_f32 v19, v20, v21
	global_store_dwordx2 v7, v[18:19], s[12:13] offset:0
	v_mul_f32_e32 v22, v22, v251
	v_mul_f32_e32 v23, v23, v251
	v_mul_f32_e32 v24, v24, v251
	v_mul_f32_e32 v25, v25, v251
	v_cvt_pk_bf16_f32 v22, v22, v23
	v_cvt_pk_bf16_f32 v23, v24, v25
	global_store_dwordx2 v200, v[22:23], s[12:13] offset:0
	v_mul_f32_e32 v26, v26, v250
	v_mul_f32_e32 v27, v27, v250
	v_mul_f32_e32 v28, v28, v250
	v_mul_f32_e32 v29, v29, v250
	v_cvt_pk_bf16_f32 v26, v26, v27
	v_cvt_pk_bf16_f32 v27, v28, v29
	global_store_dwordx2 v7, v[26:27], s[12:13] offset:32
	v_mul_f32_e32 v30, v30, v251
	v_mul_f32_e32 v31, v31, v251
	v_mul_f32_e32 v32, v32, v251
	v_mul_f32_e32 v33, v33, v251
	v_cvt_pk_bf16_f32 v30, v30, v31
	v_cvt_pk_bf16_f32 v31, v32, v33
	global_store_dwordx2 v200, v[30:31], s[12:13] offset:32
	v_mul_f32_e32 v34, v34, v250
	v_mul_f32_e32 v35, v35, v250
	v_mul_f32_e32 v36, v36, v250
	v_mul_f32_e32 v37, v37, v250
	v_cvt_pk_bf16_f32 v34, v34, v35
	v_cvt_pk_bf16_f32 v35, v36, v37
	global_store_dwordx2 v7, v[34:35], s[12:13] offset:64
	v_mul_f32_e32 v38, v38, v251
	v_mul_f32_e32 v39, v39, v251
	v_mul_f32_e32 v40, v40, v251
	v_mul_f32_e32 v41, v41, v251
	v_cvt_pk_bf16_f32 v38, v38, v39
	v_cvt_pk_bf16_f32 v39, v40, v41
	global_store_dwordx2 v200, v[38:39], s[12:13] offset:64
	v_mul_f32_e32 v42, v42, v250
	v_mul_f32_e32 v43, v43, v250
	v_mul_f32_e32 v44, v44, v250
	v_mul_f32_e32 v45, v45, v250
	v_cvt_pk_bf16_f32 v42, v42, v43
	v_cvt_pk_bf16_f32 v43, v44, v45
	global_store_dwordx2 v7, v[42:43], s[12:13] offset:96
	v_mul_f32_e32 v46, v46, v251
	v_mul_f32_e32 v47, v47, v251
	v_mul_f32_e32 v48, v48, v251
	v_mul_f32_e32 v49, v49, v251
	v_cvt_pk_bf16_f32 v46, v46, v47
	v_cvt_pk_bf16_f32 v47, v48, v49
	global_store_dwordx2 v200, v[46:47], s[12:13] offset:96
	v_mul_f32_e32 v50, v50, v250
	v_mul_f32_e32 v51, v51, v250
	v_mul_f32_e32 v52, v52, v250
	v_mul_f32_e32 v53, v53, v250
	v_cvt_pk_bf16_f32 v50, v50, v51
	v_cvt_pk_bf16_f32 v51, v52, v53
	global_store_dwordx2 v7, v[50:51], s[12:13] offset:128
	v_mul_f32_e32 v54, v54, v251
	v_mul_f32_e32 v55, v55, v251
	v_mul_f32_e32 v56, v56, v251
	v_mul_f32_e32 v57, v57, v251
	v_cvt_pk_bf16_f32 v54, v54, v55
	v_cvt_pk_bf16_f32 v55, v56, v57
	global_store_dwordx2 v200, v[54:55], s[12:13] offset:128
	v_mul_f32_e32 v58, v58, v250
	v_mul_f32_e32 v59, v59, v250
	v_mul_f32_e32 v60, v60, v250
	v_mul_f32_e32 v61, v61, v250
	v_cvt_pk_bf16_f32 v58, v58, v59
	v_cvt_pk_bf16_f32 v59, v60, v61
	global_store_dwordx2 v7, v[58:59], s[12:13] offset:160
	v_mul_f32_e32 v62, v62, v251
	v_mul_f32_e32 v63, v63, v251
	v_mul_f32_e32 v64, v64, v251
	v_mul_f32_e32 v65, v65, v251
	v_cvt_pk_bf16_f32 v62, v62, v63
	v_cvt_pk_bf16_f32 v63, v64, v65
	global_store_dwordx2 v200, v[62:63], s[12:13] offset:160
	v_mul_f32_e32 v66, v66, v250
	v_mul_f32_e32 v67, v67, v250
	v_mul_f32_e32 v68, v68, v250
	v_mul_f32_e32 v69, v69, v250
	v_cvt_pk_bf16_f32 v66, v66, v67
	v_cvt_pk_bf16_f32 v67, v68, v69
	global_store_dwordx2 v7, v[66:67], s[12:13] offset:192
	v_mul_f32_e32 v70, v70, v251
	v_mul_f32_e32 v71, v71, v251
	v_mul_f32_e32 v72, v72, v251
	v_mul_f32_e32 v73, v73, v251
	v_cvt_pk_bf16_f32 v70, v70, v71
	v_cvt_pk_bf16_f32 v71, v72, v73
	global_store_dwordx2 v200, v[70:71], s[12:13] offset:192
	v_mul_f32_e32 v74, v74, v250
	v_mul_f32_e32 v75, v75, v250
	v_mul_f32_e32 v76, v76, v250
	v_mul_f32_e32 v77, v77, v250
	v_cvt_pk_bf16_f32 v74, v74, v75
	v_cvt_pk_bf16_f32 v75, v76, v77
	global_store_dwordx2 v7, v[74:75], s[12:13] offset:224
	v_mul_f32_e32 v78, v78, v251
	v_mul_f32_e32 v79, v79, v251
	v_mul_f32_e32 v80, v80, v251
	v_mul_f32_e32 v81, v81, v251
	v_cvt_pk_bf16_f32 v78, v78, v79
	v_cvt_pk_bf16_f32 v79, v80, v81
	global_store_dwordx2 v200, v[78:79], s[12:13] offset:224
	s_add_i32 s74, s74, 1
	s_add_i32 s94, s94, 1
	s_cmp_eq_u32 s74, s66
	s_cselect_b64 s[0:1], -1, 0
	s_barrier
	s_branch .LBB0_818
